# P2(b) sample-group LayerNorm/gate item also rewritten with packed f32 ops (v_pk_add/mul/fma), on top of the packed P2(c) pass
# baseline (speedup 1.0000x reference)
.LBB0_340:
	s_or_b64 exec, exec, s[8:9]
	s_add_u32 s38, s34, 0x17200000
	v_and_b32_e32 v73, 63, v126
	s_addc_u32 s39, s35, 0
	s_mov_b32 s8, 8
	s_mov_b32 s42, 8
	s_mov_b32 s6, 9
	s_mov_b32 s40, 9
	s_mov_b32 s10, 10
	s_mov_b32 s4, 11
	s_lshr_b32 s98, s24, 3
	s_and_b32 s99, s24, 7
	s_cselect_b32 s98, 0x1000, s98
	s_cmpk_lt_i32 s26, 0x100
	s_cselect_b32 s98, s24, s98
	s_cmpk_gt_i32 s98, 0xff
	v_lshlrev_b32_e32 v72, 3, v73
	s_cbranch_scc1 .LBB0_343
	s_ashr_i32 s43, s42, 31
	v_mbcnt_hi_u32_b32 v0, -1, v165
	s_lshl_b64 s[42:43], s[42:43], 3
	v_and_b32_e32 v1, 64, v0
	s_add_u32 s42, s0, s42
	v_add_u32_e32 v1, 64, v1
	v_xor_b32_e32 v2, 1, v0
	s_addc_u32 s43, s1, s43
	s_ashr_i32 s41, s40, 31
	v_cmp_lt_i32_e32 vcc, v2, v1
	s_lshl_b64 s[40:41], s[40:41], 3
	s_add_u32 s44, s0, s40
	v_cndmask_b32_e32 v2, v0, v2, vcc
	v_lshlrev_b32_e32 v128, 2, v2
	v_xor_b32_e32 v2, 2, v0
	s_addc_u32 s45, s1, s41
	s_ashr_i32 s11, s10, 31
	v_cmp_lt_i32_e32 vcc, v2, v1
	s_lshl_b64 s[10:11], s[10:11], 3
	s_add_u32 s46, s0, s10
	v_cndmask_b32_e32 v2, v0, v2, vcc
	v_lshlrev_b32_e32 v129, 2, v2
	v_xor_b32_e32 v2, 4, v0
	s_addc_u32 s47, s1, s11
	s_ashr_i32 s5, s4, 31
	v_cmp_lt_i32_e32 vcc, v2, v1
	s_lshl_b64 s[4:5], s[4:5], 3
	s_add_u32 s4, s0, s4
	v_cndmask_b32_e32 v2, v0, v2, vcc
	v_lshlrev_b32_e32 v130, 2, v2
	v_xor_b32_e32 v2, 8, v0
	s_addc_u32 s5, s1, s5
	s_load_dwordx2 s[10:11], s[42:43], 0x0
	s_load_dwordx2 s[40:41], s[44:45], 0x0
	s_nop 0
	s_load_dwordx2 s[42:43], s[46:47], 0x0
	s_load_dwordx2 s[44:45], s[4:5], 0x0
	v_cmp_lt_i32_e32 vcc, v2, v1
	s_add_u32 s7, s20, 0x5908000
	s_addc_u32 s9, s21, 0
	v_cndmask_b32_e32 v2, v0, v2, vcc
	v_lshlrev_b32_e32 v131, 2, v2
	v_xor_b32_e32 v2, 16, v0
	v_cmp_lt_i32_e32 vcc, v2, v1
	s_lshl_b32 s3, s2, 12
	s_lshl_b32 s4, s77, 9
	v_cndmask_b32_e32 v2, v0, v2, vcc
	v_lshlrev_b32_e32 v132, 2, v2
	v_xor_b32_e32 v2, 32, v0
	v_cmp_lt_i32_e32 vcc, v2, v1
	s_add_i32 s19, s3, s4
	s_lshl_b32 s19, s98, 9
	s_lshl_b32 s3, s2, 5
	s_lshl_b32 s4, s77, 2
	v_cndmask_b32_e32 v0, v0, v2, vcc
	v_mov_b32_e32 v75, 0
	v_lshlrev_b32_e32 v74, 4, v73
	s_add_i32 s29, s3, s4
	s_lshl_b32 s29, s98, 2
	s_mov_b32 s4, 0x358637bd
	v_lshlrev_b32_e32 v133, 2, v0
	v_lshl_add_u64 v[76:77], s[14:15], 0, v[74:75]
	s_lshl_b32 s25, s26, 12
	s_lshl_b32 s47, s26, 5
	v_lshlrev_b32_e32 v78, 1, v72
	v_mov_b32_e32 v79, v75
	s_movk_i32 s64, 0x5000
	s_mov_b32 s65, 0x9000
	s_mov_b32 s66, 0xe000
	s_mov_b32 s46, 0x3a800000
	v_mov_b64_e32 v[80:81], s[4:5]
	s_mov_b32 s67, 0x800000
	v_mov_b32_e32 v134, 0x4800
	s_mov_b32 s68, s98
	s_cmpk_lg_i32 s26, 0x100
	s_cbranch_scc1 .LBB0_342
	s_waitcnt lgkmcnt(0)
	s_and_b32 s56, s98, 1
	s_lshr_b32 s57, s98, 1
	s_sub_u32 s58, 0, s56
	s_mov_b32 s59, s58
	v_and_b32_e32 v254, 63, v164
	v_lshlrev_b32_e32 v160, 2, v254
	v_lshlrev_b32_e32 v162, 4, v254
	s_lshl_b32 s60, s56, 10
	v_add_u32_e32 v163, s60, v162
	v_add_u32_e32 v162, 0x800, v162
	v_lshlrev_b32_e32 v135, 5, v254
	s_lshl_b32 s60, s56, 11
	v_add_u32_e32 v135, s60, v135
	v_lshrrev_b32_e32 v255, 5, v254
	s_lshl_b32 s60, s56, 1
	v_add_u32_e32 v255, s60, v255
	v_lshlrev_b32_e32 v252, 16, v255
	v_lshlrev_b32_e32 v253, 9, v255
	s_mul_i32 s60, s57, 0x24000
	s_add_u32 s48, s34, s60
	s_addc_u32 s49, s35, 0
	s_add_u32 s48, s48, 0x15000000
	s_addc_u32 s49, s49, 0
	s_mov_b64 s[50:51], s[48:49]
	global_load_dwordx4 v[0:3], v162, s[48:49]
	global_load_dwordx4 v[4:7], v162, s[48:49] offset:1024
	s_add_u32 s48, s48, 0x4800
	s_addc_u32 s49, s49, 0
	global_load_dwordx4 v[8:11], v162, s[48:49]
	global_load_dwordx4 v[12:15], v162, s[48:49] offset:1024
	s_add_u32 s48, s48, 0x4800
	s_addc_u32 s49, s49, 0
	global_load_dwordx4 v[16:19], v162, s[48:49]
	global_load_dwordx4 v[20:23], v162, s[48:49] offset:1024
	s_add_u32 s48, s48, 0x4800
	s_addc_u32 s49, s49, 0
	global_load_dwordx4 v[24:27], v162, s[48:49]
	global_load_dwordx4 v[28:31], v162, s[48:49] offset:1024
	s_add_u32 s48, s48, 0x4800
	s_addc_u32 s49, s49, 0
	global_load_dwordx4 v[32:35], v162, s[48:49]
	global_load_dwordx4 v[36:39], v162, s[48:49] offset:1024
	s_add_u32 s48, s48, 0x4800
	s_addc_u32 s49, s49, 0
	global_load_dwordx4 v[40:43], v162, s[48:49]
	global_load_dwordx4 v[44:47], v162, s[48:49] offset:1024
	s_add_u32 s48, s48, 0x4800
	s_addc_u32 s49, s49, 0
	global_load_dwordx4 v[48:51], v162, s[48:49]
	global_load_dwordx4 v[52:55], v162, s[48:49] offset:1024
	s_add_u32 s48, s48, 0x4800
	s_addc_u32 s49, s49, 0
	global_load_dwordx4 v[56:59], v162, s[48:49]
	global_load_dwordx4 v[60:63], v162, s[48:49] offset:1024
	global_load_dwordx4 v[64:67], v135, s[10:11]
	global_load_dwordx4 v[68:71], v135, s[10:11] offset:16
	global_load_dwordx4 v[82:85], v135, s[40:41]
	global_load_dwordx4 v[86:89], v135, s[40:41] offset:16
	global_load_dwordx4 v[90:93], v253, s[44:45]
	global_load_dwordx4 v[94:97], v253, s[44:45] offset:16
	global_load_dwordx4 v[166:169], v252, s[42:43]
	global_load_dwordx4 v[170:173], v252, s[42:43] offset:16
	global_load_dwordx4 v[174:177], v252, s[42:43] offset:512
	global_load_dwordx4 v[178:181], v252, s[42:43] offset:528
	global_load_dwordx4 v[182:185], v252, s[42:43] offset:1024
	global_load_dwordx4 v[186:189], v252, s[42:43] offset:1040
	global_load_dwordx4 v[190:193], v252, s[42:43] offset:1536
	global_load_dwordx4 v[194:197], v252, s[42:43] offset:1552
	global_load_dwordx4 v[198:201], v252, s[42:43] offset:2048
	global_load_dwordx4 v[202:205], v252, s[42:43] offset:2064
	global_load_dwordx4 v[206:209], v252, s[42:43] offset:2560
	global_load_dwordx4 v[210:213], v252, s[42:43] offset:2576
	global_load_dwordx4 v[136:139], v252, s[42:43] offset:3072
	global_load_dwordx4 v[140:143], v252, s[42:43] offset:3088
	global_load_dwordx4 v[144:147], v252, s[42:43] offset:3584
	global_load_dwordx4 v[148:151], v252, s[42:43] offset:3600
	global_load_dwordx4 v[98:101], v163, s[50:51]
	s_add_u32 s50, s50, 0x4800
	s_addc_u32 s51, s51, 0
	global_load_dwordx4 v[102:105], v163, s[50:51]
	s_add_u32 s50, s50, 0x4800
	s_addc_u32 s51, s51, 0
	global_load_dwordx4 v[106:109], v163, s[50:51]
	s_add_u32 s50, s50, 0x4800
	s_addc_u32 s51, s51, 0
	global_load_dwordx4 v[110:113], v163, s[50:51]
	s_add_u32 s50, s50, 0x4800
	s_addc_u32 s51, s51, 0
	global_load_dwordx4 v[114:117], v163, s[50:51]
	s_add_u32 s50, s50, 0x4800
	s_addc_u32 s51, s51, 0
	global_load_dwordx4 v[118:121], v163, s[50:51]
	s_add_u32 s50, s50, 0x4800
	s_addc_u32 s51, s51, 0
	global_load_dwordx4 v[122:125], v163, s[50:51]
	s_add_u32 s50, s50, 0x4800
	s_addc_u32 s51, s51, 0
	global_load_dwordx4 v[214:217], v163, s[50:51]
	s_waitcnt vmcnt(30)
	v_mov_b32_e32 v236, 0
	v_mov_b32_e32 v237, 0
	v_lshlrev_b32_e32 v152, 16, v0
	v_and_b32_e32 v153, 0xffff0000, v0
	v_lshlrev_b32_e32 v154, 16, v4
	v_and_b32_e32 v155, 0xffff0000, v4
	v_pk_add_f32 v[152:153], v[152:153], v[154:155]
	v_pk_add_f32 v[236:237], v[236:237], v[152:153]
	v_lshlrev_b32_e32 v152, 16, v1
	v_and_b32_e32 v153, 0xffff0000, v1
	v_lshlrev_b32_e32 v154, 16, v5
	v_and_b32_e32 v155, 0xffff0000, v5
	v_pk_add_f32 v[152:153], v[152:153], v[154:155]
	v_pk_add_f32 v[236:237], v[236:237], v[152:153]
	v_lshlrev_b32_e32 v152, 16, v2
	v_and_b32_e32 v153, 0xffff0000, v2
	v_lshlrev_b32_e32 v154, 16, v6
	v_and_b32_e32 v155, 0xffff0000, v6
	v_pk_add_f32 v[152:153], v[152:153], v[154:155]
	v_pk_add_f32 v[236:237], v[236:237], v[152:153]
	v_lshlrev_b32_e32 v152, 16, v3
	v_and_b32_e32 v153, 0xffff0000, v3
	v_lshlrev_b32_e32 v154, 16, v7
	v_and_b32_e32 v155, 0xffff0000, v7
	v_pk_add_f32 v[152:153], v[152:153], v[154:155]
	v_pk_add_f32 v[236:237], v[236:237], v[152:153]
	v_mov_b32_e32 v238, 0
	v_mov_b32_e32 v239, 0
	v_lshlrev_b32_e32 v152, 16, v8
	v_and_b32_e32 v153, 0xffff0000, v8
	v_lshlrev_b32_e32 v154, 16, v12
	v_and_b32_e32 v155, 0xffff0000, v12
	v_pk_add_f32 v[152:153], v[152:153], v[154:155]
	v_pk_add_f32 v[238:239], v[238:239], v[152:153]
	v_lshlrev_b32_e32 v152, 16, v9
	v_and_b32_e32 v153, 0xffff0000, v9
	v_lshlrev_b32_e32 v154, 16, v13
	v_and_b32_e32 v155, 0xffff0000, v13
	v_pk_add_f32 v[152:153], v[152:153], v[154:155]
	v_pk_add_f32 v[238:239], v[238:239], v[152:153]
	v_lshlrev_b32_e32 v152, 16, v10
	v_and_b32_e32 v153, 0xffff0000, v10
	v_lshlrev_b32_e32 v154, 16, v14
	v_and_b32_e32 v155, 0xffff0000, v14
	v_pk_add_f32 v[152:153], v[152:153], v[154:155]
	v_pk_add_f32 v[238:239], v[238:239], v[152:153]
	v_lshlrev_b32_e32 v152, 16, v11
	v_and_b32_e32 v153, 0xffff0000, v11
	v_lshlrev_b32_e32 v154, 16, v15
	v_and_b32_e32 v155, 0xffff0000, v15
	v_pk_add_f32 v[152:153], v[152:153], v[154:155]
	v_pk_add_f32 v[238:239], v[238:239], v[152:153]
	v_mov_b32_e32 v240, 0
	v_mov_b32_e32 v241, 0
	v_lshlrev_b32_e32 v152, 16, v16
	v_and_b32_e32 v153, 0xffff0000, v16
	v_lshlrev_b32_e32 v154, 16, v20
	v_and_b32_e32 v155, 0xffff0000, v20
	v_pk_add_f32 v[152:153], v[152:153], v[154:155]
	v_pk_add_f32 v[240:241], v[240:241], v[152:153]
	v_lshlrev_b32_e32 v152, 16, v17
	v_and_b32_e32 v153, 0xffff0000, v17
	v_lshlrev_b32_e32 v154, 16, v21
	v_and_b32_e32 v155, 0xffff0000, v21
	v_pk_add_f32 v[152:153], v[152:153], v[154:155]
	v_pk_add_f32 v[240:241], v[240:241], v[152:153]
	v_lshlrev_b32_e32 v152, 16, v18
	v_and_b32_e32 v153, 0xffff0000, v18
	v_lshlrev_b32_e32 v154, 16, v22
	v_and_b32_e32 v155, 0xffff0000, v22
	v_pk_add_f32 v[152:153], v[152:153], v[154:155]
	v_pk_add_f32 v[240:241], v[240:241], v[152:153]
	v_lshlrev_b32_e32 v152, 16, v19
	v_and_b32_e32 v153, 0xffff0000, v19
	v_lshlrev_b32_e32 v154, 16, v23
	v_and_b32_e32 v155, 0xffff0000, v23
	v_pk_add_f32 v[152:153], v[152:153], v[154:155]
	v_pk_add_f32 v[240:241], v[240:241], v[152:153]
	v_mov_b32_e32 v242, 0
	v_mov_b32_e32 v243, 0
	v_lshlrev_b32_e32 v152, 16, v24
	v_and_b32_e32 v153, 0xffff0000, v24
	v_lshlrev_b32_e32 v154, 16, v28
	v_and_b32_e32 v155, 0xffff0000, v28
	v_pk_add_f32 v[152:153], v[152:153], v[154:155]
	v_pk_add_f32 v[242:243], v[242:243], v[152:153]
	v_lshlrev_b32_e32 v152, 16, v25
	v_and_b32_e32 v153, 0xffff0000, v25
	v_lshlrev_b32_e32 v154, 16, v29
	v_and_b32_e32 v155, 0xffff0000, v29
	v_pk_add_f32 v[152:153], v[152:153], v[154:155]
	v_pk_add_f32 v[242:243], v[242:243], v[152:153]
	v_lshlrev_b32_e32 v152, 16, v26
	v_and_b32_e32 v153, 0xffff0000, v26
	v_lshlrev_b32_e32 v154, 16, v30
	v_and_b32_e32 v155, 0xffff0000, v30
	v_pk_add_f32 v[152:153], v[152:153], v[154:155]
	v_pk_add_f32 v[242:243], v[242:243], v[152:153]
	v_lshlrev_b32_e32 v152, 16, v27
	v_and_b32_e32 v153, 0xffff0000, v27
	v_lshlrev_b32_e32 v154, 16, v31
	v_and_b32_e32 v155, 0xffff0000, v31
	v_pk_add_f32 v[152:153], v[152:153], v[154:155]
	v_pk_add_f32 v[242:243], v[242:243], v[152:153]
	v_mov_b32_e32 v244, 0
	v_mov_b32_e32 v245, 0
	v_lshlrev_b32_e32 v152, 16, v32
	v_and_b32_e32 v153, 0xffff0000, v32
	v_lshlrev_b32_e32 v154, 16, v36
	v_and_b32_e32 v155, 0xffff0000, v36
	v_pk_add_f32 v[152:153], v[152:153], v[154:155]
	v_pk_add_f32 v[244:245], v[244:245], v[152:153]
	v_lshlrev_b32_e32 v152, 16, v33
	v_and_b32_e32 v153, 0xffff0000, v33
	v_lshlrev_b32_e32 v154, 16, v37
	v_and_b32_e32 v155, 0xffff0000, v37
	v_pk_add_f32 v[152:153], v[152:153], v[154:155]
	v_pk_add_f32 v[244:245], v[244:245], v[152:153]
	v_lshlrev_b32_e32 v152, 16, v34
	v_and_b32_e32 v153, 0xffff0000, v34
	v_lshlrev_b32_e32 v154, 16, v38
	v_and_b32_e32 v155, 0xffff0000, v38
	v_pk_add_f32 v[152:153], v[152:153], v[154:155]
	v_pk_add_f32 v[244:245], v[244:245], v[152:153]
	v_lshlrev_b32_e32 v152, 16, v35
	v_and_b32_e32 v153, 0xffff0000, v35
	v_lshlrev_b32_e32 v154, 16, v39
	v_and_b32_e32 v155, 0xffff0000, v39
	v_pk_add_f32 v[152:153], v[152:153], v[154:155]
	v_pk_add_f32 v[244:245], v[244:245], v[152:153]
	v_mov_b32_e32 v246, 0
	v_mov_b32_e32 v247, 0
	v_lshlrev_b32_e32 v152, 16, v40
	v_and_b32_e32 v153, 0xffff0000, v40
	v_lshlrev_b32_e32 v154, 16, v44
	v_and_b32_e32 v155, 0xffff0000, v44
	v_pk_add_f32 v[152:153], v[152:153], v[154:155]
	v_pk_add_f32 v[246:247], v[246:247], v[152:153]
	v_lshlrev_b32_e32 v152, 16, v41
	v_and_b32_e32 v153, 0xffff0000, v41
	v_lshlrev_b32_e32 v154, 16, v45
	v_and_b32_e32 v155, 0xffff0000, v45
	v_pk_add_f32 v[152:153], v[152:153], v[154:155]
	v_pk_add_f32 v[246:247], v[246:247], v[152:153]
	v_lshlrev_b32_e32 v152, 16, v42
	v_and_b32_e32 v153, 0xffff0000, v42
	v_lshlrev_b32_e32 v154, 16, v46
	v_and_b32_e32 v155, 0xffff0000, v46
	v_pk_add_f32 v[152:153], v[152:153], v[154:155]
	v_pk_add_f32 v[246:247], v[246:247], v[152:153]
	v_lshlrev_b32_e32 v152, 16, v43
	v_and_b32_e32 v153, 0xffff0000, v43
	v_lshlrev_b32_e32 v154, 16, v47
	v_and_b32_e32 v155, 0xffff0000, v47
	v_pk_add_f32 v[152:153], v[152:153], v[154:155]
	v_pk_add_f32 v[246:247], v[246:247], v[152:153]
	v_mov_b32_e32 v248, 0
	v_mov_b32_e32 v249, 0
	v_lshlrev_b32_e32 v152, 16, v48
	v_and_b32_e32 v153, 0xffff0000, v48
	v_lshlrev_b32_e32 v154, 16, v52
	v_and_b32_e32 v155, 0xffff0000, v52
	v_pk_add_f32 v[152:153], v[152:153], v[154:155]
	v_pk_add_f32 v[248:249], v[248:249], v[152:153]
	v_lshlrev_b32_e32 v152, 16, v49
	v_and_b32_e32 v153, 0xffff0000, v49
	v_lshlrev_b32_e32 v154, 16, v53
	v_and_b32_e32 v155, 0xffff0000, v53
	v_pk_add_f32 v[152:153], v[152:153], v[154:155]
	v_pk_add_f32 v[248:249], v[248:249], v[152:153]
	v_lshlrev_b32_e32 v152, 16, v50
	v_and_b32_e32 v153, 0xffff0000, v50
	v_lshlrev_b32_e32 v154, 16, v54
	v_and_b32_e32 v155, 0xffff0000, v54
	v_pk_add_f32 v[152:153], v[152:153], v[154:155]
	v_pk_add_f32 v[248:249], v[248:249], v[152:153]
	v_lshlrev_b32_e32 v152, 16, v51
	v_and_b32_e32 v153, 0xffff0000, v51
	v_lshlrev_b32_e32 v154, 16, v55
	v_and_b32_e32 v155, 0xffff0000, v55
	v_pk_add_f32 v[152:153], v[152:153], v[154:155]
	v_pk_add_f32 v[248:249], v[248:249], v[152:153]
	v_mov_b32_e32 v250, 0
	v_mov_b32_e32 v251, 0
	v_lshlrev_b32_e32 v152, 16, v56
	v_and_b32_e32 v153, 0xffff0000, v56
	v_lshlrev_b32_e32 v154, 16, v60
	v_and_b32_e32 v155, 0xffff0000, v60
	v_pk_add_f32 v[152:153], v[152:153], v[154:155]
	v_pk_add_f32 v[250:251], v[250:251], v[152:153]
	v_lshlrev_b32_e32 v152, 16, v57
	v_and_b32_e32 v153, 0xffff0000, v57
	v_lshlrev_b32_e32 v154, 16, v61
	v_and_b32_e32 v155, 0xffff0000, v61
	v_pk_add_f32 v[152:153], v[152:153], v[154:155]
	v_pk_add_f32 v[250:251], v[250:251], v[152:153]
	v_lshlrev_b32_e32 v152, 16, v58
	v_and_b32_e32 v153, 0xffff0000, v58
	v_lshlrev_b32_e32 v154, 16, v62
	v_and_b32_e32 v155, 0xffff0000, v62
	v_pk_add_f32 v[152:153], v[152:153], v[154:155]
	v_pk_add_f32 v[250:251], v[250:251], v[152:153]
	v_lshlrev_b32_e32 v152, 16, v59
	v_and_b32_e32 v153, 0xffff0000, v59
	v_lshlrev_b32_e32 v154, 16, v63
	v_and_b32_e32 v155, 0xffff0000, v63
	v_pk_add_f32 v[152:153], v[152:153], v[154:155]
	v_pk_add_f32 v[250:251], v[250:251], v[152:153]
	v_add_f32_e32 v218, v236, v237
	v_add_f32_e32 v219, v238, v239
	v_add_f32_e32 v220, v240, v241
	v_add_f32_e32 v221, v242, v243
	v_add_f32_e32 v222, v244, v245
	v_add_f32_e32 v223, v246, v247
	v_add_f32_e32 v224, v248, v249
	v_add_f32_e32 v225, v250, v251
	v_xor_b32_e32 v161, 4, v160
	ds_bpermute_b32 v228, v161, v218
	ds_bpermute_b32 v229, v161, v219
	ds_bpermute_b32 v230, v161, v220
	ds_bpermute_b32 v231, v161, v221
	ds_bpermute_b32 v232, v161, v222
	ds_bpermute_b32 v233, v161, v223
	ds_bpermute_b32 v234, v161, v224
	ds_bpermute_b32 v235, v161, v225
	s_waitcnt lgkmcnt(0)
	v_add_f32_e32 v218, v218, v228
	v_add_f32_e32 v219, v219, v229
	v_add_f32_e32 v220, v220, v230
	v_add_f32_e32 v221, v221, v231
	v_add_f32_e32 v222, v222, v232
	v_add_f32_e32 v223, v223, v233
	v_add_f32_e32 v224, v224, v234
	v_add_f32_e32 v225, v225, v235
	v_xor_b32_e32 v161, 8, v160
	ds_bpermute_b32 v228, v161, v218
	ds_bpermute_b32 v229, v161, v219
	ds_bpermute_b32 v230, v161, v220
	ds_bpermute_b32 v231, v161, v221
	ds_bpermute_b32 v232, v161, v222
	ds_bpermute_b32 v233, v161, v223
	ds_bpermute_b32 v234, v161, v224
	ds_bpermute_b32 v235, v161, v225
	s_waitcnt lgkmcnt(0)
	v_add_f32_e32 v218, v218, v228
	v_add_f32_e32 v219, v219, v229
	v_add_f32_e32 v220, v220, v230
	v_add_f32_e32 v221, v221, v231
	v_add_f32_e32 v222, v222, v232
	v_add_f32_e32 v223, v223, v233
	v_add_f32_e32 v224, v224, v234
	v_add_f32_e32 v225, v225, v235
	v_xor_b32_e32 v161, 16, v160
	ds_bpermute_b32 v228, v161, v218
	ds_bpermute_b32 v229, v161, v219
	ds_bpermute_b32 v230, v161, v220
	ds_bpermute_b32 v231, v161, v221
	ds_bpermute_b32 v232, v161, v222
	ds_bpermute_b32 v233, v161, v223
	ds_bpermute_b32 v234, v161, v224
	ds_bpermute_b32 v235, v161, v225
	s_waitcnt lgkmcnt(0)
	v_add_f32_e32 v218, v218, v228
	v_add_f32_e32 v219, v219, v229
	v_add_f32_e32 v220, v220, v230
	v_add_f32_e32 v221, v221, v231
	v_add_f32_e32 v222, v222, v232
	v_add_f32_e32 v223, v223, v233
	v_add_f32_e32 v224, v224, v234
	v_add_f32_e32 v225, v225, v235
	v_xor_b32_e32 v161, 32, v160
	ds_bpermute_b32 v228, v161, v218
	ds_bpermute_b32 v229, v161, v219
	ds_bpermute_b32 v230, v161, v220
	ds_bpermute_b32 v231, v161, v221
	ds_bpermute_b32 v232, v161, v222
	ds_bpermute_b32 v233, v161, v223
	ds_bpermute_b32 v234, v161, v224
	ds_bpermute_b32 v235, v161, v225
	s_waitcnt lgkmcnt(0)
	v_add_f32_e32 v218, v218, v228
	v_add_f32_e32 v219, v219, v229
	v_add_f32_e32 v220, v220, v230
	v_add_f32_e32 v221, v221, v231
	v_add_f32_e32 v222, v222, v232
	v_add_f32_e32 v223, v223, v233
	v_add_f32_e32 v224, v224, v234
	v_add_f32_e32 v225, v225, v235
	v_xor_b32_e32 v161, 64, v160
	ds_bpermute_b32 v228, v161, v218
	ds_bpermute_b32 v229, v161, v219
	ds_bpermute_b32 v230, v161, v220
	ds_bpermute_b32 v231, v161, v221
	ds_bpermute_b32 v232, v161, v222
	ds_bpermute_b32 v233, v161, v223
	ds_bpermute_b32 v234, v161, v224
	ds_bpermute_b32 v235, v161, v225
	s_waitcnt lgkmcnt(0)
	v_add_f32_e32 v218, v218, v228
	v_add_f32_e32 v219, v219, v229
	v_add_f32_e32 v220, v220, v230
	v_add_f32_e32 v221, v221, v231
	v_add_f32_e32 v222, v222, v232
	v_add_f32_e32 v223, v223, v233
	v_add_f32_e32 v224, v224, v234
	v_add_f32_e32 v225, v225, v235
	v_xor_b32_e32 v161, 128, v160
	ds_bpermute_b32 v228, v161, v218
	ds_bpermute_b32 v229, v161, v219
	ds_bpermute_b32 v230, v161, v220
	ds_bpermute_b32 v231, v161, v221
	ds_bpermute_b32 v232, v161, v222
	ds_bpermute_b32 v233, v161, v223
	ds_bpermute_b32 v234, v161, v224
	ds_bpermute_b32 v235, v161, v225
	s_waitcnt lgkmcnt(0)
	v_add_f32_e32 v218, v218, v228
	v_add_f32_e32 v219, v219, v229
	v_add_f32_e32 v220, v220, v230
	v_add_f32_e32 v221, v221, v231
	v_add_f32_e32 v222, v222, v232
	v_add_f32_e32 v223, v223, v233
	v_add_f32_e32 v224, v224, v234
	v_add_f32_e32 v225, v225, v235
	v_mov_b32_e32 v159, 0x3a800000
	v_mul_f32_e32 v218, v218, v159
	v_mul_f32_e32 v219, v219, v159
	v_mul_f32_e32 v220, v220, v159
	v_mul_f32_e32 v221, v221, v159
	v_mul_f32_e32 v222, v222, v159
	v_mul_f32_e32 v223, v223, v159
	v_mul_f32_e32 v224, v224, v159
	v_mul_f32_e32 v225, v225, v159
	v_mov_b32_e32 v236, 0
	v_mov_b32_e32 v237, 0
	v_lshlrev_b32_e32 v152, 16, v0
	v_and_b32_e32 v153, 0xffff0000, v0
	v_lshlrev_b32_e32 v154, 16, v4
	v_and_b32_e32 v155, 0xffff0000, v4
	v_pk_add_f32 v[152:153], v[152:153], v[218:219] op_sel_hi:[1,0] neg_lo:[0,1] neg_hi:[0,1]
	v_pk_add_f32 v[154:155], v[154:155], v[218:219] op_sel_hi:[1,0] neg_lo:[0,1] neg_hi:[0,1]
	v_pk_mul_f32 v[154:155], v[154:155], v[154:155]
	v_pk_fma_f32 v[154:155], v[152:153], v[152:153], v[154:155]
	v_pk_add_f32 v[236:237], v[236:237], v[154:155]
	v_lshlrev_b32_e32 v152, 16, v1
	v_and_b32_e32 v153, 0xffff0000, v1
	v_lshlrev_b32_e32 v154, 16, v5
	v_and_b32_e32 v155, 0xffff0000, v5
	v_pk_add_f32 v[152:153], v[152:153], v[218:219] op_sel_hi:[1,0] neg_lo:[0,1] neg_hi:[0,1]
	v_pk_add_f32 v[154:155], v[154:155], v[218:219] op_sel_hi:[1,0] neg_lo:[0,1] neg_hi:[0,1]
	v_pk_mul_f32 v[154:155], v[154:155], v[154:155]
	v_pk_fma_f32 v[154:155], v[152:153], v[152:153], v[154:155]
	v_pk_add_f32 v[236:237], v[236:237], v[154:155]
	v_lshlrev_b32_e32 v152, 16, v2
	v_and_b32_e32 v153, 0xffff0000, v2
	v_lshlrev_b32_e32 v154, 16, v6
	v_and_b32_e32 v155, 0xffff0000, v6
	v_pk_add_f32 v[152:153], v[152:153], v[218:219] op_sel_hi:[1,0] neg_lo:[0,1] neg_hi:[0,1]
	v_pk_add_f32 v[154:155], v[154:155], v[218:219] op_sel_hi:[1,0] neg_lo:[0,1] neg_hi:[0,1]
	v_pk_mul_f32 v[154:155], v[154:155], v[154:155]
	v_pk_fma_f32 v[154:155], v[152:153], v[152:153], v[154:155]
	v_pk_add_f32 v[236:237], v[236:237], v[154:155]
	v_lshlrev_b32_e32 v152, 16, v3
	v_and_b32_e32 v153, 0xffff0000, v3
	v_lshlrev_b32_e32 v154, 16, v7
	v_and_b32_e32 v155, 0xffff0000, v7
	v_pk_add_f32 v[152:153], v[152:153], v[218:219] op_sel_hi:[1,0] neg_lo:[0,1] neg_hi:[0,1]
	v_pk_add_f32 v[154:155], v[154:155], v[218:219] op_sel_hi:[1,0] neg_lo:[0,1] neg_hi:[0,1]
	v_pk_mul_f32 v[154:155], v[154:155], v[154:155]
	v_pk_fma_f32 v[154:155], v[152:153], v[152:153], v[154:155]
	v_pk_add_f32 v[236:237], v[236:237], v[154:155]
	v_mov_b32_e32 v238, 0
	v_mov_b32_e32 v239, 0
	v_lshlrev_b32_e32 v152, 16, v8
	v_and_b32_e32 v153, 0xffff0000, v8
	v_lshlrev_b32_e32 v154, 16, v12
	v_and_b32_e32 v155, 0xffff0000, v12
	v_pk_add_f32 v[152:153], v[152:153], v[218:219] op_sel:[0,1] neg_lo:[0,1] neg_hi:[0,1]
	v_pk_add_f32 v[154:155], v[154:155], v[218:219] op_sel:[0,1] neg_lo:[0,1] neg_hi:[0,1]
	v_pk_mul_f32 v[154:155], v[154:155], v[154:155]
	v_pk_fma_f32 v[154:155], v[152:153], v[152:153], v[154:155]
	v_pk_add_f32 v[238:239], v[238:239], v[154:155]
	v_lshlrev_b32_e32 v152, 16, v9
	v_and_b32_e32 v153, 0xffff0000, v9
	v_lshlrev_b32_e32 v154, 16, v13
	v_and_b32_e32 v155, 0xffff0000, v13
	v_pk_add_f32 v[152:153], v[152:153], v[218:219] op_sel:[0,1] neg_lo:[0,1] neg_hi:[0,1]
	v_pk_add_f32 v[154:155], v[154:155], v[218:219] op_sel:[0,1] neg_lo:[0,1] neg_hi:[0,1]
	v_pk_mul_f32 v[154:155], v[154:155], v[154:155]
	v_pk_fma_f32 v[154:155], v[152:153], v[152:153], v[154:155]
	v_pk_add_f32 v[238:239], v[238:239], v[154:155]
	v_lshlrev_b32_e32 v152, 16, v10
	v_and_b32_e32 v153, 0xffff0000, v10
	v_lshlrev_b32_e32 v154, 16, v14
	v_and_b32_e32 v155, 0xffff0000, v14
	v_pk_add_f32 v[152:153], v[152:153], v[218:219] op_sel:[0,1] neg_lo:[0,1] neg_hi:[0,1]
	v_pk_add_f32 v[154:155], v[154:155], v[218:219] op_sel:[0,1] neg_lo:[0,1] neg_hi:[0,1]
	v_pk_mul_f32 v[154:155], v[154:155], v[154:155]
	v_pk_fma_f32 v[154:155], v[152:153], v[152:153], v[154:155]
	v_pk_add_f32 v[238:239], v[238:239], v[154:155]
	v_lshlrev_b32_e32 v152, 16, v11
	v_and_b32_e32 v153, 0xffff0000, v11
	v_lshlrev_b32_e32 v154, 16, v15
	v_and_b32_e32 v155, 0xffff0000, v15
	v_pk_add_f32 v[152:153], v[152:153], v[218:219] op_sel:[0,1] neg_lo:[0,1] neg_hi:[0,1]
	v_pk_add_f32 v[154:155], v[154:155], v[218:219] op_sel:[0,1] neg_lo:[0,1] neg_hi:[0,1]
	v_pk_mul_f32 v[154:155], v[154:155], v[154:155]
	v_pk_fma_f32 v[154:155], v[152:153], v[152:153], v[154:155]
	v_pk_add_f32 v[238:239], v[238:239], v[154:155]
	v_mov_b32_e32 v240, 0
	v_mov_b32_e32 v241, 0
	v_lshlrev_b32_e32 v152, 16, v16
	v_and_b32_e32 v153, 0xffff0000, v16
	v_lshlrev_b32_e32 v154, 16, v20
	v_and_b32_e32 v155, 0xffff0000, v20
	v_pk_add_f32 v[152:153], v[152:153], v[220:221] op_sel_hi:[1,0] neg_lo:[0,1] neg_hi:[0,1]
	v_pk_add_f32 v[154:155], v[154:155], v[220:221] op_sel_hi:[1,0] neg_lo:[0,1] neg_hi:[0,1]
	v_pk_mul_f32 v[154:155], v[154:155], v[154:155]
	v_pk_fma_f32 v[154:155], v[152:153], v[152:153], v[154:155]
	v_pk_add_f32 v[240:241], v[240:241], v[154:155]
	v_lshlrev_b32_e32 v152, 16, v17
	v_and_b32_e32 v153, 0xffff0000, v17
	v_lshlrev_b32_e32 v154, 16, v21
	v_and_b32_e32 v155, 0xffff0000, v21
	v_pk_add_f32 v[152:153], v[152:153], v[220:221] op_sel_hi:[1,0] neg_lo:[0,1] neg_hi:[0,1]
	v_pk_add_f32 v[154:155], v[154:155], v[220:221] op_sel_hi:[1,0] neg_lo:[0,1] neg_hi:[0,1]
	v_pk_mul_f32 v[154:155], v[154:155], v[154:155]
	v_pk_fma_f32 v[154:155], v[152:153], v[152:153], v[154:155]
	v_pk_add_f32 v[240:241], v[240:241], v[154:155]
	v_lshlrev_b32_e32 v152, 16, v18
	v_and_b32_e32 v153, 0xffff0000, v18
	v_lshlrev_b32_e32 v154, 16, v22
	v_and_b32_e32 v155, 0xffff0000, v22
	v_pk_add_f32 v[152:153], v[152:153], v[220:221] op_sel_hi:[1,0] neg_lo:[0,1] neg_hi:[0,1]
	v_pk_add_f32 v[154:155], v[154:155], v[220:221] op_sel_hi:[1,0] neg_lo:[0,1] neg_hi:[0,1]
	v_pk_mul_f32 v[154:155], v[154:155], v[154:155]
	v_pk_fma_f32 v[154:155], v[152:153], v[152:153], v[154:155]
	v_pk_add_f32 v[240:241], v[240:241], v[154:155]
	v_lshlrev_b32_e32 v152, 16, v19
	v_and_b32_e32 v153, 0xffff0000, v19
	v_lshlrev_b32_e32 v154, 16, v23
	v_and_b32_e32 v155, 0xffff0000, v23
	v_pk_add_f32 v[152:153], v[152:153], v[220:221] op_sel_hi:[1,0] neg_lo:[0,1] neg_hi:[0,1]
	v_pk_add_f32 v[154:155], v[154:155], v[220:221] op_sel_hi:[1,0] neg_lo:[0,1] neg_hi:[0,1]
	v_pk_mul_f32 v[154:155], v[154:155], v[154:155]
	v_pk_fma_f32 v[154:155], v[152:153], v[152:153], v[154:155]
	v_pk_add_f32 v[240:241], v[240:241], v[154:155]
	v_mov_b32_e32 v242, 0
	v_mov_b32_e32 v243, 0
	v_lshlrev_b32_e32 v152, 16, v24
	v_and_b32_e32 v153, 0xffff0000, v24
	v_lshlrev_b32_e32 v154, 16, v28
	v_and_b32_e32 v155, 0xffff0000, v28
	v_pk_add_f32 v[152:153], v[152:153], v[220:221] op_sel:[0,1] neg_lo:[0,1] neg_hi:[0,1]
	v_pk_add_f32 v[154:155], v[154:155], v[220:221] op_sel:[0,1] neg_lo:[0,1] neg_hi:[0,1]
	v_pk_mul_f32 v[154:155], v[154:155], v[154:155]
	v_pk_fma_f32 v[154:155], v[152:153], v[152:153], v[154:155]
	v_pk_add_f32 v[242:243], v[242:243], v[154:155]
	v_lshlrev_b32_e32 v152, 16, v25
	v_and_b32_e32 v153, 0xffff0000, v25
	v_lshlrev_b32_e32 v154, 16, v29
	v_and_b32_e32 v155, 0xffff0000, v29
	v_pk_add_f32 v[152:153], v[152:153], v[220:221] op_sel:[0,1] neg_lo:[0,1] neg_hi:[0,1]
	v_pk_add_f32 v[154:155], v[154:155], v[220:221] op_sel:[0,1] neg_lo:[0,1] neg_hi:[0,1]
	v_pk_mul_f32 v[154:155], v[154:155], v[154:155]
	v_pk_fma_f32 v[154:155], v[152:153], v[152:153], v[154:155]
	v_pk_add_f32 v[242:243], v[242:243], v[154:155]
	v_lshlrev_b32_e32 v152, 16, v26
	v_and_b32_e32 v153, 0xffff0000, v26
	v_lshlrev_b32_e32 v154, 16, v30
	v_and_b32_e32 v155, 0xffff0000, v30
	v_pk_add_f32 v[152:153], v[152:153], v[220:221] op_sel:[0,1] neg_lo:[0,1] neg_hi:[0,1]
	v_pk_add_f32 v[154:155], v[154:155], v[220:221] op_sel:[0,1] neg_lo:[0,1] neg_hi:[0,1]
	v_pk_mul_f32 v[154:155], v[154:155], v[154:155]
	v_pk_fma_f32 v[154:155], v[152:153], v[152:153], v[154:155]
	v_pk_add_f32 v[242:243], v[242:243], v[154:155]
	v_lshlrev_b32_e32 v152, 16, v27
	v_and_b32_e32 v153, 0xffff0000, v27
	v_lshlrev_b32_e32 v154, 16, v31
	v_and_b32_e32 v155, 0xffff0000, v31
	v_pk_add_f32 v[152:153], v[152:153], v[220:221] op_sel:[0,1] neg_lo:[0,1] neg_hi:[0,1]
	v_pk_add_f32 v[154:155], v[154:155], v[220:221] op_sel:[0,1] neg_lo:[0,1] neg_hi:[0,1]
	v_pk_mul_f32 v[154:155], v[154:155], v[154:155]
	v_pk_fma_f32 v[154:155], v[152:153], v[152:153], v[154:155]
	v_pk_add_f32 v[242:243], v[242:243], v[154:155]
	v_mov_b32_e32 v244, 0
	v_mov_b32_e32 v245, 0
	v_lshlrev_b32_e32 v152, 16, v32
	v_and_b32_e32 v153, 0xffff0000, v32
	v_lshlrev_b32_e32 v154, 16, v36
	v_and_b32_e32 v155, 0xffff0000, v36
	v_pk_add_f32 v[152:153], v[152:153], v[222:223] op_sel_hi:[1,0] neg_lo:[0,1] neg_hi:[0,1]
	v_pk_add_f32 v[154:155], v[154:155], v[222:223] op_sel_hi:[1,0] neg_lo:[0,1] neg_hi:[0,1]
	v_pk_mul_f32 v[154:155], v[154:155], v[154:155]
	v_pk_fma_f32 v[154:155], v[152:153], v[152:153], v[154:155]
	v_pk_add_f32 v[244:245], v[244:245], v[154:155]
	v_lshlrev_b32_e32 v152, 16, v33
	v_and_b32_e32 v153, 0xffff0000, v33
	v_lshlrev_b32_e32 v154, 16, v37
	v_and_b32_e32 v155, 0xffff0000, v37
	v_pk_add_f32 v[152:153], v[152:153], v[222:223] op_sel_hi:[1,0] neg_lo:[0,1] neg_hi:[0,1]
	v_pk_add_f32 v[154:155], v[154:155], v[222:223] op_sel_hi:[1,0] neg_lo:[0,1] neg_hi:[0,1]
	v_pk_mul_f32 v[154:155], v[154:155], v[154:155]
	v_pk_fma_f32 v[154:155], v[152:153], v[152:153], v[154:155]
	v_pk_add_f32 v[244:245], v[244:245], v[154:155]
	v_lshlrev_b32_e32 v152, 16, v34
	v_and_b32_e32 v153, 0xffff0000, v34
	v_lshlrev_b32_e32 v154, 16, v38
	v_and_b32_e32 v155, 0xffff0000, v38
	v_pk_add_f32 v[152:153], v[152:153], v[222:223] op_sel_hi:[1,0] neg_lo:[0,1] neg_hi:[0,1]
	v_pk_add_f32 v[154:155], v[154:155], v[222:223] op_sel_hi:[1,0] neg_lo:[0,1] neg_hi:[0,1]
	v_pk_mul_f32 v[154:155], v[154:155], v[154:155]
	v_pk_fma_f32 v[154:155], v[152:153], v[152:153], v[154:155]
	v_pk_add_f32 v[244:245], v[244:245], v[154:155]
	v_lshlrev_b32_e32 v152, 16, v35
	v_and_b32_e32 v153, 0xffff0000, v35
	v_lshlrev_b32_e32 v154, 16, v39
	v_and_b32_e32 v155, 0xffff0000, v39
	v_pk_add_f32 v[152:153], v[152:153], v[222:223] op_sel_hi:[1,0] neg_lo:[0,1] neg_hi:[0,1]
	v_pk_add_f32 v[154:155], v[154:155], v[222:223] op_sel_hi:[1,0] neg_lo:[0,1] neg_hi:[0,1]
	v_pk_mul_f32 v[154:155], v[154:155], v[154:155]
	v_pk_fma_f32 v[154:155], v[152:153], v[152:153], v[154:155]
	v_pk_add_f32 v[244:245], v[244:245], v[154:155]
	v_mov_b32_e32 v246, 0
	v_mov_b32_e32 v247, 0
	v_lshlrev_b32_e32 v152, 16, v40
	v_and_b32_e32 v153, 0xffff0000, v40
	v_lshlrev_b32_e32 v154, 16, v44
	v_and_b32_e32 v155, 0xffff0000, v44
	v_pk_add_f32 v[152:153], v[152:153], v[222:223] op_sel:[0,1] neg_lo:[0,1] neg_hi:[0,1]
	v_pk_add_f32 v[154:155], v[154:155], v[222:223] op_sel:[0,1] neg_lo:[0,1] neg_hi:[0,1]
	v_pk_mul_f32 v[154:155], v[154:155], v[154:155]
	v_pk_fma_f32 v[154:155], v[152:153], v[152:153], v[154:155]
	v_pk_add_f32 v[246:247], v[246:247], v[154:155]
	v_lshlrev_b32_e32 v152, 16, v41
	v_and_b32_e32 v153, 0xffff0000, v41
	v_lshlrev_b32_e32 v154, 16, v45
	v_and_b32_e32 v155, 0xffff0000, v45
	v_pk_add_f32 v[152:153], v[152:153], v[222:223] op_sel:[0,1] neg_lo:[0,1] neg_hi:[0,1]
	v_pk_add_f32 v[154:155], v[154:155], v[222:223] op_sel:[0,1] neg_lo:[0,1] neg_hi:[0,1]
	v_pk_mul_f32 v[154:155], v[154:155], v[154:155]
	v_pk_fma_f32 v[154:155], v[152:153], v[152:153], v[154:155]
	v_pk_add_f32 v[246:247], v[246:247], v[154:155]
	v_lshlrev_b32_e32 v152, 16, v42
	v_and_b32_e32 v153, 0xffff0000, v42
	v_lshlrev_b32_e32 v154, 16, v46
	v_and_b32_e32 v155, 0xffff0000, v46
	v_pk_add_f32 v[152:153], v[152:153], v[222:223] op_sel:[0,1] neg_lo:[0,1] neg_hi:[0,1]
	v_pk_add_f32 v[154:155], v[154:155], v[222:223] op_sel:[0,1] neg_lo:[0,1] neg_hi:[0,1]
	v_pk_mul_f32 v[154:155], v[154:155], v[154:155]
	v_pk_fma_f32 v[154:155], v[152:153], v[152:153], v[154:155]
	v_pk_add_f32 v[246:247], v[246:247], v[154:155]
	v_lshlrev_b32_e32 v152, 16, v43
	v_and_b32_e32 v153, 0xffff0000, v43
	v_lshlrev_b32_e32 v154, 16, v47
	v_and_b32_e32 v155, 0xffff0000, v47
	v_pk_add_f32 v[152:153], v[152:153], v[222:223] op_sel:[0,1] neg_lo:[0,1] neg_hi:[0,1]
	v_pk_add_f32 v[154:155], v[154:155], v[222:223] op_sel:[0,1] neg_lo:[0,1] neg_hi:[0,1]
	v_pk_mul_f32 v[154:155], v[154:155], v[154:155]
	v_pk_fma_f32 v[154:155], v[152:153], v[152:153], v[154:155]
	v_pk_add_f32 v[246:247], v[246:247], v[154:155]
	v_mov_b32_e32 v248, 0
	v_mov_b32_e32 v249, 0
	v_lshlrev_b32_e32 v152, 16, v48
	v_and_b32_e32 v153, 0xffff0000, v48
	v_lshlrev_b32_e32 v154, 16, v52
	v_and_b32_e32 v155, 0xffff0000, v52
	v_pk_add_f32 v[152:153], v[152:153], v[224:225] op_sel_hi:[1,0] neg_lo:[0,1] neg_hi:[0,1]
	v_pk_add_f32 v[154:155], v[154:155], v[224:225] op_sel_hi:[1,0] neg_lo:[0,1] neg_hi:[0,1]
	v_pk_mul_f32 v[154:155], v[154:155], v[154:155]
	v_pk_fma_f32 v[154:155], v[152:153], v[152:153], v[154:155]
	v_pk_add_f32 v[248:249], v[248:249], v[154:155]
	v_lshlrev_b32_e32 v152, 16, v49
	v_and_b32_e32 v153, 0xffff0000, v49
	v_lshlrev_b32_e32 v154, 16, v53
	v_and_b32_e32 v155, 0xffff0000, v53
	v_pk_add_f32 v[152:153], v[152:153], v[224:225] op_sel_hi:[1,0] neg_lo:[0,1] neg_hi:[0,1]
	v_pk_add_f32 v[154:155], v[154:155], v[224:225] op_sel_hi:[1,0] neg_lo:[0,1] neg_hi:[0,1]
	v_pk_mul_f32 v[154:155], v[154:155], v[154:155]
	v_pk_fma_f32 v[154:155], v[152:153], v[152:153], v[154:155]
	v_pk_add_f32 v[248:249], v[248:249], v[154:155]
	v_lshlrev_b32_e32 v152, 16, v50
	v_and_b32_e32 v153, 0xffff0000, v50
	v_lshlrev_b32_e32 v154, 16, v54
	v_and_b32_e32 v155, 0xffff0000, v54
	v_pk_add_f32 v[152:153], v[152:153], v[224:225] op_sel_hi:[1,0] neg_lo:[0,1] neg_hi:[0,1]
	v_pk_add_f32 v[154:155], v[154:155], v[224:225] op_sel_hi:[1,0] neg_lo:[0,1] neg_hi:[0,1]
	v_pk_mul_f32 v[154:155], v[154:155], v[154:155]
	v_pk_fma_f32 v[154:155], v[152:153], v[152:153], v[154:155]
	v_pk_add_f32 v[248:249], v[248:249], v[154:155]
	v_lshlrev_b32_e32 v152, 16, v51
	v_and_b32_e32 v153, 0xffff0000, v51
	v_lshlrev_b32_e32 v154, 16, v55
	v_and_b32_e32 v155, 0xffff0000, v55
	v_pk_add_f32 v[152:153], v[152:153], v[224:225] op_sel_hi:[1,0] neg_lo:[0,1] neg_hi:[0,1]
	v_pk_add_f32 v[154:155], v[154:155], v[224:225] op_sel_hi:[1,0] neg_lo:[0,1] neg_hi:[0,1]
	v_pk_mul_f32 v[154:155], v[154:155], v[154:155]
	v_pk_fma_f32 v[154:155], v[152:153], v[152:153], v[154:155]
	v_pk_add_f32 v[248:249], v[248:249], v[154:155]
	v_mov_b32_e32 v250, 0
	v_mov_b32_e32 v251, 0
	v_lshlrev_b32_e32 v152, 16, v56
	v_and_b32_e32 v153, 0xffff0000, v56
	v_lshlrev_b32_e32 v154, 16, v60
	v_and_b32_e32 v155, 0xffff0000, v60
	v_pk_add_f32 v[152:153], v[152:153], v[224:225] op_sel:[0,1] neg_lo:[0,1] neg_hi:[0,1]
	v_pk_add_f32 v[154:155], v[154:155], v[224:225] op_sel:[0,1] neg_lo:[0,1] neg_hi:[0,1]
	v_pk_mul_f32 v[154:155], v[154:155], v[154:155]
	v_pk_fma_f32 v[154:155], v[152:153], v[152:153], v[154:155]
	v_pk_add_f32 v[250:251], v[250:251], v[154:155]
	v_lshlrev_b32_e32 v152, 16, v57
	v_and_b32_e32 v153, 0xffff0000, v57
	v_lshlrev_b32_e32 v154, 16, v61
	v_and_b32_e32 v155, 0xffff0000, v61
	v_pk_add_f32 v[152:153], v[152:153], v[224:225] op_sel:[0,1] neg_lo:[0,1] neg_hi:[0,1]
	v_pk_add_f32 v[154:155], v[154:155], v[224:225] op_sel:[0,1] neg_lo:[0,1] neg_hi:[0,1]
	v_pk_mul_f32 v[154:155], v[154:155], v[154:155]
	v_pk_fma_f32 v[154:155], v[152:153], v[152:153], v[154:155]
	v_pk_add_f32 v[250:251], v[250:251], v[154:155]
	v_lshlrev_b32_e32 v152, 16, v58
	v_and_b32_e32 v153, 0xffff0000, v58
	v_lshlrev_b32_e32 v154, 16, v62
	v_and_b32_e32 v155, 0xffff0000, v62
	v_pk_add_f32 v[152:153], v[152:153], v[224:225] op_sel:[0,1] neg_lo:[0,1] neg_hi:[0,1]
	v_pk_add_f32 v[154:155], v[154:155], v[224:225] op_sel:[0,1] neg_lo:[0,1] neg_hi:[0,1]
	v_pk_mul_f32 v[154:155], v[154:155], v[154:155]
	v_pk_fma_f32 v[154:155], v[152:153], v[152:153], v[154:155]
	v_pk_add_f32 v[250:251], v[250:251], v[154:155]
	v_lshlrev_b32_e32 v152, 16, v59
	v_and_b32_e32 v153, 0xffff0000, v59
	v_lshlrev_b32_e32 v154, 16, v63
	v_and_b32_e32 v155, 0xffff0000, v63
	v_pk_add_f32 v[152:153], v[152:153], v[224:225] op_sel:[0,1] neg_lo:[0,1] neg_hi:[0,1]
	v_pk_add_f32 v[154:155], v[154:155], v[224:225] op_sel:[0,1] neg_lo:[0,1] neg_hi:[0,1]
	v_pk_mul_f32 v[154:155], v[154:155], v[154:155]
	v_pk_fma_f32 v[154:155], v[152:153], v[152:153], v[154:155]
	v_pk_add_f32 v[250:251], v[250:251], v[154:155]
	v_add_f32_e32 v228, v236, v237
	v_add_f32_e32 v229, v238, v239
	v_add_f32_e32 v230, v240, v241
	v_add_f32_e32 v231, v242, v243
	v_add_f32_e32 v232, v244, v245
	v_add_f32_e32 v233, v246, v247
	v_add_f32_e32 v234, v248, v249
	v_add_f32_e32 v235, v250, v251
	v_xor_b32_e32 v161, 4, v160
	ds_bpermute_b32 v236, v161, v228
	ds_bpermute_b32 v237, v161, v229
	ds_bpermute_b32 v238, v161, v230
	ds_bpermute_b32 v239, v161, v231
	ds_bpermute_b32 v240, v161, v232
	ds_bpermute_b32 v241, v161, v233
	ds_bpermute_b32 v242, v161, v234
	ds_bpermute_b32 v243, v161, v235
	s_waitcnt lgkmcnt(0)
	v_add_f32_e32 v228, v228, v236
	v_add_f32_e32 v229, v229, v237
	v_add_f32_e32 v230, v230, v238
	v_add_f32_e32 v231, v231, v239
	v_add_f32_e32 v232, v232, v240
	v_add_f32_e32 v233, v233, v241
	v_add_f32_e32 v234, v234, v242
	v_add_f32_e32 v235, v235, v243
	v_xor_b32_e32 v161, 8, v160
	ds_bpermute_b32 v236, v161, v228
	ds_bpermute_b32 v237, v161, v229
	ds_bpermute_b32 v238, v161, v230
	ds_bpermute_b32 v239, v161, v231
	ds_bpermute_b32 v240, v161, v232
	ds_bpermute_b32 v241, v161, v233
	ds_bpermute_b32 v242, v161, v234
	ds_bpermute_b32 v243, v161, v235
	s_waitcnt lgkmcnt(0)
	v_add_f32_e32 v228, v228, v236
	v_add_f32_e32 v229, v229, v237
	v_add_f32_e32 v230, v230, v238
	v_add_f32_e32 v231, v231, v239
	v_add_f32_e32 v232, v232, v240
	v_add_f32_e32 v233, v233, v241
	v_add_f32_e32 v234, v234, v242
	v_add_f32_e32 v235, v235, v243
	v_xor_b32_e32 v161, 16, v160
	ds_bpermute_b32 v236, v161, v228
	ds_bpermute_b32 v237, v161, v229
	ds_bpermute_b32 v238, v161, v230
	ds_bpermute_b32 v239, v161, v231
	ds_bpermute_b32 v240, v161, v232
	ds_bpermute_b32 v241, v161, v233
	ds_bpermute_b32 v242, v161, v234
	ds_bpermute_b32 v243, v161, v235
	s_waitcnt lgkmcnt(0)
	v_add_f32_e32 v228, v228, v236
	v_add_f32_e32 v229, v229, v237
	v_add_f32_e32 v230, v230, v238
	v_add_f32_e32 v231, v231, v239
	v_add_f32_e32 v232, v232, v240
	v_add_f32_e32 v233, v233, v241
	v_add_f32_e32 v234, v234, v242
	v_add_f32_e32 v235, v235, v243
	v_xor_b32_e32 v161, 32, v160
	ds_bpermute_b32 v236, v161, v228
	ds_bpermute_b32 v237, v161, v229
	ds_bpermute_b32 v238, v161, v230
	ds_bpermute_b32 v239, v161, v231
	ds_bpermute_b32 v240, v161, v232
	ds_bpermute_b32 v241, v161, v233
	ds_bpermute_b32 v242, v161, v234
	ds_bpermute_b32 v243, v161, v235
	s_waitcnt lgkmcnt(0)
	v_add_f32_e32 v228, v228, v236
	v_add_f32_e32 v229, v229, v237
	v_add_f32_e32 v230, v230, v238
	v_add_f32_e32 v231, v231, v239
	v_add_f32_e32 v232, v232, v240
	v_add_f32_e32 v233, v233, v241
	v_add_f32_e32 v234, v234, v242
	v_add_f32_e32 v235, v235, v243
	v_xor_b32_e32 v161, 64, v160
	ds_bpermute_b32 v236, v161, v228
	ds_bpermute_b32 v237, v161, v229
	ds_bpermute_b32 v238, v161, v230
	ds_bpermute_b32 v239, v161, v231
	ds_bpermute_b32 v240, v161, v232
	ds_bpermute_b32 v241, v161, v233
	ds_bpermute_b32 v242, v161, v234
	ds_bpermute_b32 v243, v161, v235
	s_waitcnt lgkmcnt(0)
	v_add_f32_e32 v228, v228, v236
	v_add_f32_e32 v229, v229, v237
	v_add_f32_e32 v230, v230, v238
	v_add_f32_e32 v231, v231, v239
	v_add_f32_e32 v232, v232, v240
	v_add_f32_e32 v233, v233, v241
	v_add_f32_e32 v234, v234, v242
	v_add_f32_e32 v235, v235, v243
	v_xor_b32_e32 v161, 128, v160
	ds_bpermute_b32 v236, v161, v228
	ds_bpermute_b32 v237, v161, v229
	ds_bpermute_b32 v238, v161, v230
	ds_bpermute_b32 v239, v161, v231
	ds_bpermute_b32 v240, v161, v232
	ds_bpermute_b32 v241, v161, v233
	ds_bpermute_b32 v242, v161, v234
	ds_bpermute_b32 v243, v161, v235
	s_waitcnt lgkmcnt(0)
	v_add_f32_e32 v228, v228, v236
	v_add_f32_e32 v229, v229, v237
	v_add_f32_e32 v230, v230, v238
	v_add_f32_e32 v231, v231, v239
	v_add_f32_e32 v232, v232, v240
	v_add_f32_e32 v233, v233, v241
	v_add_f32_e32 v234, v234, v242
	v_add_f32_e32 v235, v235, v243
	v_mov_b32_e32 v158, 0x358637bd
	v_fma_f32 v228, v228, v159, v158
	v_rsq_f32_e32 v228, v228
	v_fma_f32 v229, v229, v159, v158
	v_rsq_f32_e32 v229, v229
	v_fma_f32 v230, v230, v159, v158
	v_rsq_f32_e32 v230, v230
	v_fma_f32 v231, v231, v159, v158
	v_rsq_f32_e32 v231, v231
	v_fma_f32 v232, v232, v159, v158
	v_rsq_f32_e32 v232, v232
	v_fma_f32 v233, v233, v159, v158
	v_rsq_f32_e32 v233, v233
	v_fma_f32 v234, v234, v159, v158
	v_rsq_f32_e32 v234, v234
	v_fma_f32 v235, v235, v159, v158
	v_rsq_f32_e32 v235, v235
	s_waitcnt vmcnt(26)
	v_cndmask_b32_e64 v152, v0, v4, s[58:59]
	v_cndmask_b32_e64 v153, v1, v5, s[58:59]
	v_cndmask_b32_e64 v154, v2, v6, s[58:59]
	v_cndmask_b32_e64 v155, v3, v7, s[58:59]
	v_lshlrev_b32_e32 v156, 16, v152
	v_and_b32_e32 v157, 0xffff0000, v152
	v_pk_add_f32 v[156:157], v[156:157], v[218:219] op_sel_hi:[1,0] neg_lo:[0,1] neg_hi:[0,1]
	v_pk_mul_f32 v[156:157], v[156:157], v[228:229] op_sel_hi:[1,0]
	v_pk_fma_f32 v[0:1], v[156:157], v[64:65], v[82:83]
	v_lshlrev_b32_e32 v156, 16, v153
	v_and_b32_e32 v157, 0xffff0000, v153
	v_pk_add_f32 v[156:157], v[156:157], v[218:219] op_sel_hi:[1,0] neg_lo:[0,1] neg_hi:[0,1]
	v_pk_mul_f32 v[156:157], v[156:157], v[228:229] op_sel_hi:[1,0]
	v_pk_fma_f32 v[2:3], v[156:157], v[66:67], v[84:85]
	v_lshlrev_b32_e32 v156, 16, v154
	v_and_b32_e32 v157, 0xffff0000, v154
	v_pk_add_f32 v[156:157], v[156:157], v[218:219] op_sel_hi:[1,0] neg_lo:[0,1] neg_hi:[0,1]
	v_pk_mul_f32 v[156:157], v[156:157], v[228:229] op_sel_hi:[1,0]
	v_pk_fma_f32 v[4:5], v[156:157], v[68:69], v[86:87]
	v_lshlrev_b32_e32 v156, 16, v155
	v_and_b32_e32 v157, 0xffff0000, v155
	v_pk_add_f32 v[156:157], v[156:157], v[218:219] op_sel_hi:[1,0] neg_lo:[0,1] neg_hi:[0,1]
	v_pk_mul_f32 v[156:157], v[156:157], v[228:229] op_sel_hi:[1,0]
	v_pk_fma_f32 v[6:7], v[156:157], v[70:71], v[88:89]
	v_cndmask_b32_e64 v152, v8, v12, s[58:59]
	v_cndmask_b32_e64 v153, v9, v13, s[58:59]
	v_cndmask_b32_e64 v154, v10, v14, s[58:59]
	v_cndmask_b32_e64 v155, v11, v15, s[58:59]
	v_lshlrev_b32_e32 v156, 16, v152
	v_and_b32_e32 v157, 0xffff0000, v152
	v_pk_add_f32 v[156:157], v[156:157], v[218:219] op_sel:[0,1] neg_lo:[0,1] neg_hi:[0,1]
	v_pk_mul_f32 v[156:157], v[156:157], v[228:229] op_sel:[0,1]
	v_pk_fma_f32 v[8:9], v[156:157], v[64:65], v[82:83]
	v_lshlrev_b32_e32 v156, 16, v153
	v_and_b32_e32 v157, 0xffff0000, v153
	v_pk_add_f32 v[156:157], v[156:157], v[218:219] op_sel:[0,1] neg_lo:[0,1] neg_hi:[0,1]
	v_pk_mul_f32 v[156:157], v[156:157], v[228:229] op_sel:[0,1]
	v_pk_fma_f32 v[10:11], v[156:157], v[66:67], v[84:85]
	v_lshlrev_b32_e32 v156, 16, v154
	v_and_b32_e32 v157, 0xffff0000, v154
	v_pk_add_f32 v[156:157], v[156:157], v[218:219] op_sel:[0,1] neg_lo:[0,1] neg_hi:[0,1]
	v_pk_mul_f32 v[156:157], v[156:157], v[228:229] op_sel:[0,1]
	v_pk_fma_f32 v[12:13], v[156:157], v[68:69], v[86:87]
	v_lshlrev_b32_e32 v156, 16, v155
	v_and_b32_e32 v157, 0xffff0000, v155
	v_pk_add_f32 v[156:157], v[156:157], v[218:219] op_sel:[0,1] neg_lo:[0,1] neg_hi:[0,1]
	v_pk_mul_f32 v[156:157], v[156:157], v[228:229] op_sel:[0,1]
	v_pk_fma_f32 v[14:15], v[156:157], v[70:71], v[88:89]
	v_cndmask_b32_e64 v152, v16, v20, s[58:59]
	v_cndmask_b32_e64 v153, v17, v21, s[58:59]
	v_cndmask_b32_e64 v154, v18, v22, s[58:59]
	v_cndmask_b32_e64 v155, v19, v23, s[58:59]
	v_lshlrev_b32_e32 v156, 16, v152
	v_and_b32_e32 v157, 0xffff0000, v152
	v_pk_add_f32 v[156:157], v[156:157], v[220:221] op_sel_hi:[1,0] neg_lo:[0,1] neg_hi:[0,1]
	v_pk_mul_f32 v[156:157], v[156:157], v[230:231] op_sel_hi:[1,0]
	v_pk_fma_f32 v[16:17], v[156:157], v[64:65], v[82:83]
	v_lshlrev_b32_e32 v156, 16, v153
	v_and_b32_e32 v157, 0xffff0000, v153
	v_pk_add_f32 v[156:157], v[156:157], v[220:221] op_sel_hi:[1,0] neg_lo:[0,1] neg_hi:[0,1]
	v_pk_mul_f32 v[156:157], v[156:157], v[230:231] op_sel_hi:[1,0]
	v_pk_fma_f32 v[18:19], v[156:157], v[66:67], v[84:85]
	v_lshlrev_b32_e32 v156, 16, v154
	v_and_b32_e32 v157, 0xffff0000, v154
	v_pk_add_f32 v[156:157], v[156:157], v[220:221] op_sel_hi:[1,0] neg_lo:[0,1] neg_hi:[0,1]
	v_pk_mul_f32 v[156:157], v[156:157], v[230:231] op_sel_hi:[1,0]
	v_pk_fma_f32 v[20:21], v[156:157], v[68:69], v[86:87]
	v_lshlrev_b32_e32 v156, 16, v155
	v_and_b32_e32 v157, 0xffff0000, v155
	v_pk_add_f32 v[156:157], v[156:157], v[220:221] op_sel_hi:[1,0] neg_lo:[0,1] neg_hi:[0,1]
	v_pk_mul_f32 v[156:157], v[156:157], v[230:231] op_sel_hi:[1,0]
	v_pk_fma_f32 v[22:23], v[156:157], v[70:71], v[88:89]
	v_cndmask_b32_e64 v152, v24, v28, s[58:59]
	v_cndmask_b32_e64 v153, v25, v29, s[58:59]
	v_cndmask_b32_e64 v154, v26, v30, s[58:59]
	v_cndmask_b32_e64 v155, v27, v31, s[58:59]
	v_lshlrev_b32_e32 v156, 16, v152
	v_and_b32_e32 v157, 0xffff0000, v152
	v_pk_add_f32 v[156:157], v[156:157], v[220:221] op_sel:[0,1] neg_lo:[0,1] neg_hi:[0,1]
	v_pk_mul_f32 v[156:157], v[156:157], v[230:231] op_sel:[0,1]
	v_pk_fma_f32 v[24:25], v[156:157], v[64:65], v[82:83]
	v_lshlrev_b32_e32 v156, 16, v153
	v_and_b32_e32 v157, 0xffff0000, v153
	v_pk_add_f32 v[156:157], v[156:157], v[220:221] op_sel:[0,1] neg_lo:[0,1] neg_hi:[0,1]
	v_pk_mul_f32 v[156:157], v[156:157], v[230:231] op_sel:[0,1]
	v_pk_fma_f32 v[26:27], v[156:157], v[66:67], v[84:85]
	v_lshlrev_b32_e32 v156, 16, v154
	v_and_b32_e32 v157, 0xffff0000, v154
	v_pk_add_f32 v[156:157], v[156:157], v[220:221] op_sel:[0,1] neg_lo:[0,1] neg_hi:[0,1]
	v_pk_mul_f32 v[156:157], v[156:157], v[230:231] op_sel:[0,1]
	v_pk_fma_f32 v[28:29], v[156:157], v[68:69], v[86:87]
	v_lshlrev_b32_e32 v156, 16, v155
	v_and_b32_e32 v157, 0xffff0000, v155
	v_pk_add_f32 v[156:157], v[156:157], v[220:221] op_sel:[0,1] neg_lo:[0,1] neg_hi:[0,1]
	v_pk_mul_f32 v[156:157], v[156:157], v[230:231] op_sel:[0,1]
	v_pk_fma_f32 v[30:31], v[156:157], v[70:71], v[88:89]
	v_cndmask_b32_e64 v152, v32, v36, s[58:59]
	v_cndmask_b32_e64 v153, v33, v37, s[58:59]
	v_cndmask_b32_e64 v154, v34, v38, s[58:59]
	v_cndmask_b32_e64 v155, v35, v39, s[58:59]
	v_lshlrev_b32_e32 v156, 16, v152
	v_and_b32_e32 v157, 0xffff0000, v152
	v_pk_add_f32 v[156:157], v[156:157], v[222:223] op_sel_hi:[1,0] neg_lo:[0,1] neg_hi:[0,1]
	v_pk_mul_f32 v[156:157], v[156:157], v[232:233] op_sel_hi:[1,0]
	v_pk_fma_f32 v[32:33], v[156:157], v[64:65], v[82:83]
	v_lshlrev_b32_e32 v156, 16, v153
	v_and_b32_e32 v157, 0xffff0000, v153
	v_pk_add_f32 v[156:157], v[156:157], v[222:223] op_sel_hi:[1,0] neg_lo:[0,1] neg_hi:[0,1]
	v_pk_mul_f32 v[156:157], v[156:157], v[232:233] op_sel_hi:[1,0]
	v_pk_fma_f32 v[34:35], v[156:157], v[66:67], v[84:85]
	v_lshlrev_b32_e32 v156, 16, v154
	v_and_b32_e32 v157, 0xffff0000, v154
	v_pk_add_f32 v[156:157], v[156:157], v[222:223] op_sel_hi:[1,0] neg_lo:[0,1] neg_hi:[0,1]
	v_pk_mul_f32 v[156:157], v[156:157], v[232:233] op_sel_hi:[1,0]
	v_pk_fma_f32 v[36:37], v[156:157], v[68:69], v[86:87]
	v_lshlrev_b32_e32 v156, 16, v155
	v_and_b32_e32 v157, 0xffff0000, v155
	v_pk_add_f32 v[156:157], v[156:157], v[222:223] op_sel_hi:[1,0] neg_lo:[0,1] neg_hi:[0,1]
	v_pk_mul_f32 v[156:157], v[156:157], v[232:233] op_sel_hi:[1,0]
	v_pk_fma_f32 v[38:39], v[156:157], v[70:71], v[88:89]
	v_cndmask_b32_e64 v152, v40, v44, s[58:59]
	v_cndmask_b32_e64 v153, v41, v45, s[58:59]
	v_cndmask_b32_e64 v154, v42, v46, s[58:59]
	v_cndmask_b32_e64 v155, v43, v47, s[58:59]
	v_lshlrev_b32_e32 v156, 16, v152
	v_and_b32_e32 v157, 0xffff0000, v152
	v_pk_add_f32 v[156:157], v[156:157], v[222:223] op_sel:[0,1] neg_lo:[0,1] neg_hi:[0,1]
	v_pk_mul_f32 v[156:157], v[156:157], v[232:233] op_sel:[0,1]
	v_pk_fma_f32 v[40:41], v[156:157], v[64:65], v[82:83]
	v_lshlrev_b32_e32 v156, 16, v153
	v_and_b32_e32 v157, 0xffff0000, v153
	v_pk_add_f32 v[156:157], v[156:157], v[222:223] op_sel:[0,1] neg_lo:[0,1] neg_hi:[0,1]
	v_pk_mul_f32 v[156:157], v[156:157], v[232:233] op_sel:[0,1]
	v_pk_fma_f32 v[42:43], v[156:157], v[66:67], v[84:85]
	v_lshlrev_b32_e32 v156, 16, v154
	v_and_b32_e32 v157, 0xffff0000, v154
	v_pk_add_f32 v[156:157], v[156:157], v[222:223] op_sel:[0,1] neg_lo:[0,1] neg_hi:[0,1]
	v_pk_mul_f32 v[156:157], v[156:157], v[232:233] op_sel:[0,1]
	v_pk_fma_f32 v[44:45], v[156:157], v[68:69], v[86:87]
	v_lshlrev_b32_e32 v156, 16, v155
	v_and_b32_e32 v157, 0xffff0000, v155
	v_pk_add_f32 v[156:157], v[156:157], v[222:223] op_sel:[0,1] neg_lo:[0,1] neg_hi:[0,1]
	v_pk_mul_f32 v[156:157], v[156:157], v[232:233] op_sel:[0,1]
	v_pk_fma_f32 v[46:47], v[156:157], v[70:71], v[88:89]
	v_cndmask_b32_e64 v152, v48, v52, s[58:59]
	v_cndmask_b32_e64 v153, v49, v53, s[58:59]
	v_cndmask_b32_e64 v154, v50, v54, s[58:59]
	v_cndmask_b32_e64 v155, v51, v55, s[58:59]
	v_lshlrev_b32_e32 v156, 16, v152
	v_and_b32_e32 v157, 0xffff0000, v152
	v_pk_add_f32 v[156:157], v[156:157], v[224:225] op_sel_hi:[1,0] neg_lo:[0,1] neg_hi:[0,1]
	v_pk_mul_f32 v[156:157], v[156:157], v[234:235] op_sel_hi:[1,0]
	v_pk_fma_f32 v[48:49], v[156:157], v[64:65], v[82:83]
	v_lshlrev_b32_e32 v156, 16, v153
	v_and_b32_e32 v157, 0xffff0000, v153
	v_pk_add_f32 v[156:157], v[156:157], v[224:225] op_sel_hi:[1,0] neg_lo:[0,1] neg_hi:[0,1]
	v_pk_mul_f32 v[156:157], v[156:157], v[234:235] op_sel_hi:[1,0]
	v_pk_fma_f32 v[50:51], v[156:157], v[66:67], v[84:85]
	v_lshlrev_b32_e32 v156, 16, v154
	v_and_b32_e32 v157, 0xffff0000, v154
	v_pk_add_f32 v[156:157], v[156:157], v[224:225] op_sel_hi:[1,0] neg_lo:[0,1] neg_hi:[0,1]
	v_pk_mul_f32 v[156:157], v[156:157], v[234:235] op_sel_hi:[1,0]
	v_pk_fma_f32 v[52:53], v[156:157], v[68:69], v[86:87]
	v_lshlrev_b32_e32 v156, 16, v155
	v_and_b32_e32 v157, 0xffff0000, v155
	v_pk_add_f32 v[156:157], v[156:157], v[224:225] op_sel_hi:[1,0] neg_lo:[0,1] neg_hi:[0,1]
	v_pk_mul_f32 v[156:157], v[156:157], v[234:235] op_sel_hi:[1,0]
	v_pk_fma_f32 v[54:55], v[156:157], v[70:71], v[88:89]
	v_cndmask_b32_e64 v152, v56, v60, s[58:59]
	v_cndmask_b32_e64 v153, v57, v61, s[58:59]
	v_cndmask_b32_e64 v154, v58, v62, s[58:59]
	v_cndmask_b32_e64 v155, v59, v63, s[58:59]
	v_lshlrev_b32_e32 v156, 16, v152
	v_and_b32_e32 v157, 0xffff0000, v152
	v_pk_add_f32 v[156:157], v[156:157], v[224:225] op_sel:[0,1] neg_lo:[0,1] neg_hi:[0,1]
	v_pk_mul_f32 v[156:157], v[156:157], v[234:235] op_sel:[0,1]
	v_pk_fma_f32 v[56:57], v[156:157], v[64:65], v[82:83]
	v_lshlrev_b32_e32 v156, 16, v153
	v_and_b32_e32 v157, 0xffff0000, v153
	v_pk_add_f32 v[156:157], v[156:157], v[224:225] op_sel:[0,1] neg_lo:[0,1] neg_hi:[0,1]
	v_pk_mul_f32 v[156:157], v[156:157], v[234:235] op_sel:[0,1]
	v_pk_fma_f32 v[58:59], v[156:157], v[66:67], v[84:85]
	v_lshlrev_b32_e32 v156, 16, v154
	v_and_b32_e32 v157, 0xffff0000, v154
	v_pk_add_f32 v[156:157], v[156:157], v[224:225] op_sel:[0,1] neg_lo:[0,1] neg_hi:[0,1]
	v_pk_mul_f32 v[156:157], v[156:157], v[234:235] op_sel:[0,1]
	v_pk_fma_f32 v[60:61], v[156:157], v[68:69], v[86:87]
	v_lshlrev_b32_e32 v156, 16, v155
	v_and_b32_e32 v157, 0xffff0000, v155
	v_pk_add_f32 v[156:157], v[156:157], v[224:225] op_sel:[0,1] neg_lo:[0,1] neg_hi:[0,1]
	v_pk_mul_f32 v[156:157], v[156:157], v[234:235] op_sel:[0,1]
	v_pk_fma_f32 v[62:63], v[156:157], v[70:71], v[88:89]
	s_waitcnt vmcnt(0)
	s_lshl_b32 s60, s57, 15
	s_add_u32 s54, s38, s60
	s_addc_u32 s55, s39, 0
	s_add_u32 s54, s54, 0x2000000
	s_addc_u32 s55, s55, 0
	v_mov_b32_e32 v152, v90
	v_mov_b32_e32 v153, v90
	v_mov_b32_e32 v154, v90
	v_mov_b32_e32 v155, v90
	v_mov_b32_e32 v156, v90
	v_mov_b32_e32 v157, v90
	v_mov_b32_e32 v158, v90
	v_mov_b32_e32 v159, v90
	v_pk_fma_f32 v[152:153], v[0:1], v[166:167], v[152:153] op_sel_hi:[1,0,1]
	v_pk_fma_f32 v[154:155], v[2:3], v[166:167], v[154:155] op_sel_hi:[1,0,1]
	v_pk_fma_f32 v[156:157], v[4:5], v[166:167], v[156:157] op_sel_hi:[1,0,1]
	v_pk_fma_f32 v[158:159], v[6:7], v[166:167], v[158:159] op_sel_hi:[1,0,1]
	v_lshlrev_b32_e32 v244, 16, v98
	v_and_b32_e32 v245, 0xffff0000, v98
	v_pk_mul_f32 v[244:245], v[244:245], v[152:153]
	v_cvt_pk_bf16_f32 v98, v244, v245
	v_lshlrev_b32_e32 v244, 16, v99
	v_and_b32_e32 v245, 0xffff0000, v99
	v_pk_mul_f32 v[244:245], v[244:245], v[154:155]
	v_cvt_pk_bf16_f32 v99, v244, v245
	v_lshlrev_b32_e32 v244, 16, v100
	v_and_b32_e32 v245, 0xffff0000, v100
	v_pk_mul_f32 v[244:245], v[244:245], v[156:157]
	v_cvt_pk_bf16_f32 v100, v244, v245
	v_lshlrev_b32_e32 v244, 16, v101
	v_and_b32_e32 v245, 0xffff0000, v101
	v_pk_mul_f32 v[244:245], v[244:245], v[158:159]
	v_cvt_pk_bf16_f32 v101, v244, v245
	global_store_dwordx4 v163, v[98:101], s[54:55]
	s_add_u32 s54, s54, 0x1000
	s_addc_u32 s55, s55, 0
	v_mov_b32_e32 v152, v91
	v_mov_b32_e32 v153, v91
	v_mov_b32_e32 v154, v91
	v_mov_b32_e32 v155, v91
	v_mov_b32_e32 v156, v91
	v_mov_b32_e32 v157, v91
	v_mov_b32_e32 v158, v91
	v_mov_b32_e32 v159, v91
	v_pk_fma_f32 v[152:153], v[0:1], v[174:175], v[152:153] op_sel_hi:[1,0,1]
	v_pk_fma_f32 v[154:155], v[2:3], v[174:175], v[154:155] op_sel_hi:[1,0,1]
	v_pk_fma_f32 v[156:157], v[4:5], v[174:175], v[156:157] op_sel_hi:[1,0,1]
	v_pk_fma_f32 v[158:159], v[6:7], v[174:175], v[158:159] op_sel_hi:[1,0,1]
	v_pk_fma_f32 v[152:153], v[8:9], v[174:175], v[152:153] op_sel:[0,1,0]
	v_pk_fma_f32 v[154:155], v[10:11], v[174:175], v[154:155] op_sel:[0,1,0]
	v_pk_fma_f32 v[156:157], v[12:13], v[174:175], v[156:157] op_sel:[0,1,0]
	v_pk_fma_f32 v[158:159], v[14:15], v[174:175], v[158:159] op_sel:[0,1,0]
	v_lshlrev_b32_e32 v244, 16, v102
	v_and_b32_e32 v245, 0xffff0000, v102
	v_pk_mul_f32 v[244:245], v[244:245], v[152:153]
	v_cvt_pk_bf16_f32 v102, v244, v245
	v_lshlrev_b32_e32 v244, 16, v103
	v_and_b32_e32 v245, 0xffff0000, v103
	v_pk_mul_f32 v[244:245], v[244:245], v[154:155]
	v_cvt_pk_bf16_f32 v103, v244, v245
	v_lshlrev_b32_e32 v244, 16, v104
	v_and_b32_e32 v245, 0xffff0000, v104
	v_pk_mul_f32 v[244:245], v[244:245], v[156:157]
	v_cvt_pk_bf16_f32 v104, v244, v245
	v_lshlrev_b32_e32 v244, 16, v105
	v_and_b32_e32 v245, 0xffff0000, v105
	v_pk_mul_f32 v[244:245], v[244:245], v[158:159]
	v_cvt_pk_bf16_f32 v105, v244, v245
	global_store_dwordx4 v163, v[102:105], s[54:55]
	s_add_u32 s54, s54, 0x1000
	s_addc_u32 s55, s55, 0
	v_mov_b32_e32 v152, v92
	v_mov_b32_e32 v153, v92
	v_mov_b32_e32 v154, v92
	v_mov_b32_e32 v155, v92
	v_mov_b32_e32 v156, v92
	v_mov_b32_e32 v157, v92
	v_mov_b32_e32 v158, v92
	v_mov_b32_e32 v159, v92
	v_pk_fma_f32 v[152:153], v[0:1], v[182:183], v[152:153] op_sel_hi:[1,0,1]
	v_pk_fma_f32 v[154:155], v[2:3], v[182:183], v[154:155] op_sel_hi:[1,0,1]
	v_pk_fma_f32 v[156:157], v[4:5], v[182:183], v[156:157] op_sel_hi:[1,0,1]
	v_pk_fma_f32 v[158:159], v[6:7], v[182:183], v[158:159] op_sel_hi:[1,0,1]
	v_pk_fma_f32 v[152:153], v[8:9], v[182:183], v[152:153] op_sel:[0,1,0]
	v_pk_fma_f32 v[154:155], v[10:11], v[182:183], v[154:155] op_sel:[0,1,0]
	v_pk_fma_f32 v[156:157], v[12:13], v[182:183], v[156:157] op_sel:[0,1,0]
	v_pk_fma_f32 v[158:159], v[14:15], v[182:183], v[158:159] op_sel:[0,1,0]
	v_pk_fma_f32 v[152:153], v[16:17], v[184:185], v[152:153] op_sel_hi:[1,0,1]
	v_pk_fma_f32 v[154:155], v[18:19], v[184:185], v[154:155] op_sel_hi:[1,0,1]
	v_pk_fma_f32 v[156:157], v[20:21], v[184:185], v[156:157] op_sel_hi:[1,0,1]
	v_pk_fma_f32 v[158:159], v[22:23], v[184:185], v[158:159] op_sel_hi:[1,0,1]
	v_lshlrev_b32_e32 v244, 16, v106
	v_and_b32_e32 v245, 0xffff0000, v106
	v_pk_mul_f32 v[244:245], v[244:245], v[152:153]
	v_cvt_pk_bf16_f32 v106, v244, v245
	v_lshlrev_b32_e32 v244, 16, v107
	v_and_b32_e32 v245, 0xffff0000, v107
	v_pk_mul_f32 v[244:245], v[244:245], v[154:155]
	v_cvt_pk_bf16_f32 v107, v244, v245
	v_lshlrev_b32_e32 v244, 16, v108
	v_and_b32_e32 v245, 0xffff0000, v108
	v_pk_mul_f32 v[244:245], v[244:245], v[156:157]
	v_cvt_pk_bf16_f32 v108, v244, v245
	v_lshlrev_b32_e32 v244, 16, v109
	v_and_b32_e32 v245, 0xffff0000, v109
	v_pk_mul_f32 v[244:245], v[244:245], v[158:159]
	v_cvt_pk_bf16_f32 v109, v244, v245
	global_store_dwordx4 v163, v[106:109], s[54:55]
	s_add_u32 s54, s54, 0x1000
	s_addc_u32 s55, s55, 0
	v_mov_b32_e32 v152, v93
	v_mov_b32_e32 v153, v93
	v_mov_b32_e32 v154, v93
	v_mov_b32_e32 v155, v93
	v_mov_b32_e32 v156, v93
	v_mov_b32_e32 v157, v93
	v_mov_b32_e32 v158, v93
	v_mov_b32_e32 v159, v93
	v_pk_fma_f32 v[152:153], v[0:1], v[190:191], v[152:153] op_sel_hi:[1,0,1]
	v_pk_fma_f32 v[154:155], v[2:3], v[190:191], v[154:155] op_sel_hi:[1,0,1]
	v_pk_fma_f32 v[156:157], v[4:5], v[190:191], v[156:157] op_sel_hi:[1,0,1]
	v_pk_fma_f32 v[158:159], v[6:7], v[190:191], v[158:159] op_sel_hi:[1,0,1]
	v_pk_fma_f32 v[152:153], v[8:9], v[190:191], v[152:153] op_sel:[0,1,0]
	v_pk_fma_f32 v[154:155], v[10:11], v[190:191], v[154:155] op_sel:[0,1,0]
	v_pk_fma_f32 v[156:157], v[12:13], v[190:191], v[156:157] op_sel:[0,1,0]
	v_pk_fma_f32 v[158:159], v[14:15], v[190:191], v[158:159] op_sel:[0,1,0]
	v_pk_fma_f32 v[152:153], v[16:17], v[192:193], v[152:153] op_sel_hi:[1,0,1]
	v_pk_fma_f32 v[154:155], v[18:19], v[192:193], v[154:155] op_sel_hi:[1,0,1]
	v_pk_fma_f32 v[156:157], v[20:21], v[192:193], v[156:157] op_sel_hi:[1,0,1]
	v_pk_fma_f32 v[158:159], v[22:23], v[192:193], v[158:159] op_sel_hi:[1,0,1]
	v_pk_fma_f32 v[152:153], v[24:25], v[192:193], v[152:153] op_sel:[0,1,0]
	v_pk_fma_f32 v[154:155], v[26:27], v[192:193], v[154:155] op_sel:[0,1,0]
	v_pk_fma_f32 v[156:157], v[28:29], v[192:193], v[156:157] op_sel:[0,1,0]
	v_pk_fma_f32 v[158:159], v[30:31], v[192:193], v[158:159] op_sel:[0,1,0]
	v_lshlrev_b32_e32 v244, 16, v110
	v_and_b32_e32 v245, 0xffff0000, v110
	v_pk_mul_f32 v[244:245], v[244:245], v[152:153]
	v_cvt_pk_bf16_f32 v110, v244, v245
	v_lshlrev_b32_e32 v244, 16, v111
	v_and_b32_e32 v245, 0xffff0000, v111
	v_pk_mul_f32 v[244:245], v[244:245], v[154:155]
	v_cvt_pk_bf16_f32 v111, v244, v245
	v_lshlrev_b32_e32 v244, 16, v112
	v_and_b32_e32 v245, 0xffff0000, v112
	v_pk_mul_f32 v[244:245], v[244:245], v[156:157]
	v_cvt_pk_bf16_f32 v112, v244, v245
	v_lshlrev_b32_e32 v244, 16, v113
	v_and_b32_e32 v245, 0xffff0000, v113
	v_pk_mul_f32 v[244:245], v[244:245], v[158:159]
	v_cvt_pk_bf16_f32 v113, v244, v245
	global_store_dwordx4 v163, v[110:113], s[54:55]
	s_add_u32 s54, s54, 0x1000
	s_addc_u32 s55, s55, 0
	v_mov_b32_e32 v152, v94
	v_mov_b32_e32 v153, v94
	v_mov_b32_e32 v154, v94
	v_mov_b32_e32 v155, v94
	v_mov_b32_e32 v156, v94
	v_mov_b32_e32 v157, v94
	v_mov_b32_e32 v158, v94
	v_mov_b32_e32 v159, v94
	v_pk_fma_f32 v[152:153], v[0:1], v[198:199], v[152:153] op_sel_hi:[1,0,1]
	v_pk_fma_f32 v[154:155], v[2:3], v[198:199], v[154:155] op_sel_hi:[1,0,1]
	v_pk_fma_f32 v[156:157], v[4:5], v[198:199], v[156:157] op_sel_hi:[1,0,1]
	v_pk_fma_f32 v[158:159], v[6:7], v[198:199], v[158:159] op_sel_hi:[1,0,1]
	v_pk_fma_f32 v[152:153], v[8:9], v[198:199], v[152:153] op_sel:[0,1,0]
	v_pk_fma_f32 v[154:155], v[10:11], v[198:199], v[154:155] op_sel:[0,1,0]
	v_pk_fma_f32 v[156:157], v[12:13], v[198:199], v[156:157] op_sel:[0,1,0]
	v_pk_fma_f32 v[158:159], v[14:15], v[198:199], v[158:159] op_sel:[0,1,0]
	v_pk_fma_f32 v[152:153], v[16:17], v[200:201], v[152:153] op_sel_hi:[1,0,1]
	v_pk_fma_f32 v[154:155], v[18:19], v[200:201], v[154:155] op_sel_hi:[1,0,1]
	v_pk_fma_f32 v[156:157], v[20:21], v[200:201], v[156:157] op_sel_hi:[1,0,1]
	v_pk_fma_f32 v[158:159], v[22:23], v[200:201], v[158:159] op_sel_hi:[1,0,1]
	v_pk_fma_f32 v[152:153], v[24:25], v[200:201], v[152:153] op_sel:[0,1,0]
	v_pk_fma_f32 v[154:155], v[26:27], v[200:201], v[154:155] op_sel:[0,1,0]
	v_pk_fma_f32 v[156:157], v[28:29], v[200:201], v[156:157] op_sel:[0,1,0]
	v_pk_fma_f32 v[158:159], v[30:31], v[200:201], v[158:159] op_sel:[0,1,0]
	v_pk_fma_f32 v[152:153], v[32:33], v[202:203], v[152:153] op_sel_hi:[1,0,1]
	v_pk_fma_f32 v[154:155], v[34:35], v[202:203], v[154:155] op_sel_hi:[1,0,1]
	v_pk_fma_f32 v[156:157], v[36:37], v[202:203], v[156:157] op_sel_hi:[1,0,1]
	v_pk_fma_f32 v[158:159], v[38:39], v[202:203], v[158:159] op_sel_hi:[1,0,1]
	v_lshlrev_b32_e32 v244, 16, v114
	v_and_b32_e32 v245, 0xffff0000, v114
	v_pk_mul_f32 v[244:245], v[244:245], v[152:153]
	v_cvt_pk_bf16_f32 v114, v244, v245
	v_lshlrev_b32_e32 v244, 16, v115
	v_and_b32_e32 v245, 0xffff0000, v115
	v_pk_mul_f32 v[244:245], v[244:245], v[154:155]
	v_cvt_pk_bf16_f32 v115, v244, v245
	v_lshlrev_b32_e32 v244, 16, v116
	v_and_b32_e32 v245, 0xffff0000, v116
	v_pk_mul_f32 v[244:245], v[244:245], v[156:157]
	v_cvt_pk_bf16_f32 v116, v244, v245
	v_lshlrev_b32_e32 v244, 16, v117
	v_and_b32_e32 v245, 0xffff0000, v117
	v_pk_mul_f32 v[244:245], v[244:245], v[158:159]
	v_cvt_pk_bf16_f32 v117, v244, v245
	global_store_dwordx4 v163, v[114:117], s[54:55]
	s_add_u32 s54, s54, 0x1000
	s_addc_u32 s55, s55, 0
	v_mov_b32_e32 v152, v95
	v_mov_b32_e32 v153, v95
	v_mov_b32_e32 v154, v95
	v_mov_b32_e32 v155, v95
	v_mov_b32_e32 v156, v95
	v_mov_b32_e32 v157, v95
	v_mov_b32_e32 v158, v95
	v_mov_b32_e32 v159, v95
	v_pk_fma_f32 v[152:153], v[0:1], v[206:207], v[152:153] op_sel_hi:[1,0,1]
	v_pk_fma_f32 v[154:155], v[2:3], v[206:207], v[154:155] op_sel_hi:[1,0,1]
	v_pk_fma_f32 v[156:157], v[4:5], v[206:207], v[156:157] op_sel_hi:[1,0,1]
	v_pk_fma_f32 v[158:159], v[6:7], v[206:207], v[158:159] op_sel_hi:[1,0,1]
	v_pk_fma_f32 v[152:153], v[8:9], v[206:207], v[152:153] op_sel:[0,1,0]
	v_pk_fma_f32 v[154:155], v[10:11], v[206:207], v[154:155] op_sel:[0,1,0]
	v_pk_fma_f32 v[156:157], v[12:13], v[206:207], v[156:157] op_sel:[0,1,0]
	v_pk_fma_f32 v[158:159], v[14:15], v[206:207], v[158:159] op_sel:[0,1,0]
	v_pk_fma_f32 v[152:153], v[16:17], v[208:209], v[152:153] op_sel_hi:[1,0,1]
	v_pk_fma_f32 v[154:155], v[18:19], v[208:209], v[154:155] op_sel_hi:[1,0,1]
	v_pk_fma_f32 v[156:157], v[20:21], v[208:209], v[156:157] op_sel_hi:[1,0,1]
	v_pk_fma_f32 v[158:159], v[22:23], v[208:209], v[158:159] op_sel_hi:[1,0,1]
	v_pk_fma_f32 v[152:153], v[24:25], v[208:209], v[152:153] op_sel:[0,1,0]
	v_pk_fma_f32 v[154:155], v[26:27], v[208:209], v[154:155] op_sel:[0,1,0]
	v_pk_fma_f32 v[156:157], v[28:29], v[208:209], v[156:157] op_sel:[0,1,0]
	v_pk_fma_f32 v[158:159], v[30:31], v[208:209], v[158:159] op_sel:[0,1,0]
	v_pk_fma_f32 v[152:153], v[32:33], v[210:211], v[152:153] op_sel_hi:[1,0,1]
	v_pk_fma_f32 v[154:155], v[34:35], v[210:211], v[154:155] op_sel_hi:[1,0,1]
	v_pk_fma_f32 v[156:157], v[36:37], v[210:211], v[156:157] op_sel_hi:[1,0,1]
	v_pk_fma_f32 v[158:159], v[38:39], v[210:211], v[158:159] op_sel_hi:[1,0,1]
	v_pk_fma_f32 v[152:153], v[40:41], v[210:211], v[152:153] op_sel:[0,1,0]
	v_pk_fma_f32 v[154:155], v[42:43], v[210:211], v[154:155] op_sel:[0,1,0]
	v_pk_fma_f32 v[156:157], v[44:45], v[210:211], v[156:157] op_sel:[0,1,0]
	v_pk_fma_f32 v[158:159], v[46:47], v[210:211], v[158:159] op_sel:[0,1,0]
	v_lshlrev_b32_e32 v244, 16, v118
	v_and_b32_e32 v245, 0xffff0000, v118
	v_pk_mul_f32 v[244:245], v[244:245], v[152:153]
	v_cvt_pk_bf16_f32 v118, v244, v245
	v_lshlrev_b32_e32 v244, 16, v119
	v_and_b32_e32 v245, 0xffff0000, v119
	v_pk_mul_f32 v[244:245], v[244:245], v[154:155]
	v_cvt_pk_bf16_f32 v119, v244, v245
	v_lshlrev_b32_e32 v244, 16, v120
	v_and_b32_e32 v245, 0xffff0000, v120
	v_pk_mul_f32 v[244:245], v[244:245], v[156:157]
	v_cvt_pk_bf16_f32 v120, v244, v245
	v_lshlrev_b32_e32 v244, 16, v121
	v_and_b32_e32 v245, 0xffff0000, v121
	v_pk_mul_f32 v[244:245], v[244:245], v[158:159]
	v_cvt_pk_bf16_f32 v121, v244, v245
	global_store_dwordx4 v163, v[118:121], s[54:55]
	s_add_u32 s54, s54, 0x1000
	s_addc_u32 s55, s55, 0
	v_mov_b32_e32 v152, v96
	v_mov_b32_e32 v153, v96
	v_mov_b32_e32 v154, v96
	v_mov_b32_e32 v155, v96
	v_mov_b32_e32 v156, v96
	v_mov_b32_e32 v157, v96
	v_mov_b32_e32 v158, v96
	v_mov_b32_e32 v159, v96
	v_pk_fma_f32 v[152:153], v[0:1], v[136:137], v[152:153] op_sel_hi:[1,0,1]
	v_pk_fma_f32 v[154:155], v[2:3], v[136:137], v[154:155] op_sel_hi:[1,0,1]
	v_pk_fma_f32 v[156:157], v[4:5], v[136:137], v[156:157] op_sel_hi:[1,0,1]
	v_pk_fma_f32 v[158:159], v[6:7], v[136:137], v[158:159] op_sel_hi:[1,0,1]
	v_pk_fma_f32 v[152:153], v[8:9], v[136:137], v[152:153] op_sel:[0,1,0]
	v_pk_fma_f32 v[154:155], v[10:11], v[136:137], v[154:155] op_sel:[0,1,0]
	v_pk_fma_f32 v[156:157], v[12:13], v[136:137], v[156:157] op_sel:[0,1,0]
	v_pk_fma_f32 v[158:159], v[14:15], v[136:137], v[158:159] op_sel:[0,1,0]
	v_pk_fma_f32 v[152:153], v[16:17], v[138:139], v[152:153] op_sel_hi:[1,0,1]
	v_pk_fma_f32 v[154:155], v[18:19], v[138:139], v[154:155] op_sel_hi:[1,0,1]
	v_pk_fma_f32 v[156:157], v[20:21], v[138:139], v[156:157] op_sel_hi:[1,0,1]
	v_pk_fma_f32 v[158:159], v[22:23], v[138:139], v[158:159] op_sel_hi:[1,0,1]
	v_pk_fma_f32 v[152:153], v[24:25], v[138:139], v[152:153] op_sel:[0,1,0]
	v_pk_fma_f32 v[154:155], v[26:27], v[138:139], v[154:155] op_sel:[0,1,0]
	v_pk_fma_f32 v[156:157], v[28:29], v[138:139], v[156:157] op_sel:[0,1,0]
	v_pk_fma_f32 v[158:159], v[30:31], v[138:139], v[158:159] op_sel:[0,1,0]
	v_pk_fma_f32 v[152:153], v[32:33], v[140:141], v[152:153] op_sel_hi:[1,0,1]
	v_pk_fma_f32 v[154:155], v[34:35], v[140:141], v[154:155] op_sel_hi:[1,0,1]
	v_pk_fma_f32 v[156:157], v[36:37], v[140:141], v[156:157] op_sel_hi:[1,0,1]
	v_pk_fma_f32 v[158:159], v[38:39], v[140:141], v[158:159] op_sel_hi:[1,0,1]
	v_pk_fma_f32 v[152:153], v[40:41], v[140:141], v[152:153] op_sel:[0,1,0]
	v_pk_fma_f32 v[154:155], v[42:43], v[140:141], v[154:155] op_sel:[0,1,0]
	v_pk_fma_f32 v[156:157], v[44:45], v[140:141], v[156:157] op_sel:[0,1,0]
	v_pk_fma_f32 v[158:159], v[46:47], v[140:141], v[158:159] op_sel:[0,1,0]
	v_pk_fma_f32 v[152:153], v[48:49], v[142:143], v[152:153] op_sel_hi:[1,0,1]
	v_pk_fma_f32 v[154:155], v[50:51], v[142:143], v[154:155] op_sel_hi:[1,0,1]
	v_pk_fma_f32 v[156:157], v[52:53], v[142:143], v[156:157] op_sel_hi:[1,0,1]
	v_pk_fma_f32 v[158:159], v[54:55], v[142:143], v[158:159] op_sel_hi:[1,0,1]
	v_lshlrev_b32_e32 v244, 16, v122
	v_and_b32_e32 v245, 0xffff0000, v122
	v_pk_mul_f32 v[244:245], v[244:245], v[152:153]
	v_cvt_pk_bf16_f32 v122, v244, v245
	v_lshlrev_b32_e32 v244, 16, v123
	v_and_b32_e32 v245, 0xffff0000, v123
	v_pk_mul_f32 v[244:245], v[244:245], v[154:155]
	v_cvt_pk_bf16_f32 v123, v244, v245
	v_lshlrev_b32_e32 v244, 16, v124
	v_and_b32_e32 v245, 0xffff0000, v124
	v_pk_mul_f32 v[244:245], v[244:245], v[156:157]
	v_cvt_pk_bf16_f32 v124, v244, v245
	v_lshlrev_b32_e32 v244, 16, v125
	v_and_b32_e32 v245, 0xffff0000, v125
	v_pk_mul_f32 v[244:245], v[244:245], v[158:159]
	v_cvt_pk_bf16_f32 v125, v244, v245
	global_store_dwordx4 v163, v[122:125], s[54:55]
	s_add_u32 s54, s54, 0x1000
	s_addc_u32 s55, s55, 0
	v_mov_b32_e32 v152, v97
	v_mov_b32_e32 v153, v97
	v_mov_b32_e32 v154, v97
	v_mov_b32_e32 v155, v97
	v_mov_b32_e32 v156, v97
	v_mov_b32_e32 v157, v97
	v_mov_b32_e32 v158, v97
	v_mov_b32_e32 v159, v97
	v_pk_fma_f32 v[152:153], v[0:1], v[144:145], v[152:153] op_sel_hi:[1,0,1]
	v_pk_fma_f32 v[154:155], v[2:3], v[144:145], v[154:155] op_sel_hi:[1,0,1]
	v_pk_fma_f32 v[156:157], v[4:5], v[144:145], v[156:157] op_sel_hi:[1,0,1]
	v_pk_fma_f32 v[158:159], v[6:7], v[144:145], v[158:159] op_sel_hi:[1,0,1]
	v_pk_fma_f32 v[152:153], v[8:9], v[144:145], v[152:153] op_sel:[0,1,0]
	v_pk_fma_f32 v[154:155], v[10:11], v[144:145], v[154:155] op_sel:[0,1,0]
	v_pk_fma_f32 v[156:157], v[12:13], v[144:145], v[156:157] op_sel:[0,1,0]
	v_pk_fma_f32 v[158:159], v[14:15], v[144:145], v[158:159] op_sel:[0,1,0]
	v_pk_fma_f32 v[152:153], v[16:17], v[146:147], v[152:153] op_sel_hi:[1,0,1]
	v_pk_fma_f32 v[154:155], v[18:19], v[146:147], v[154:155] op_sel_hi:[1,0,1]
	v_pk_fma_f32 v[156:157], v[20:21], v[146:147], v[156:157] op_sel_hi:[1,0,1]
	v_pk_fma_f32 v[158:159], v[22:23], v[146:147], v[158:159] op_sel_hi:[1,0,1]
	v_pk_fma_f32 v[152:153], v[24:25], v[146:147], v[152:153] op_sel:[0,1,0]
	v_pk_fma_f32 v[154:155], v[26:27], v[146:147], v[154:155] op_sel:[0,1,0]
	v_pk_fma_f32 v[156:157], v[28:29], v[146:147], v[156:157] op_sel:[0,1,0]
	v_pk_fma_f32 v[158:159], v[30:31], v[146:147], v[158:159] op_sel:[0,1,0]
	v_pk_fma_f32 v[152:153], v[32:33], v[148:149], v[152:153] op_sel_hi:[1,0,1]
	v_pk_fma_f32 v[154:155], v[34:35], v[148:149], v[154:155] op_sel_hi:[1,0,1]
	v_pk_fma_f32 v[156:157], v[36:37], v[148:149], v[156:157] op_sel_hi:[1,0,1]
	v_pk_fma_f32 v[158:159], v[38:39], v[148:149], v[158:159] op_sel_hi:[1,0,1]
	v_pk_fma_f32 v[152:153], v[40:41], v[148:149], v[152:153] op_sel:[0,1,0]
	v_pk_fma_f32 v[154:155], v[42:43], v[148:149], v[154:155] op_sel:[0,1,0]
	v_pk_fma_f32 v[156:157], v[44:45], v[148:149], v[156:157] op_sel:[0,1,0]
	v_pk_fma_f32 v[158:159], v[46:47], v[148:149], v[158:159] op_sel:[0,1,0]
	v_pk_fma_f32 v[152:153], v[48:49], v[150:151], v[152:153] op_sel_hi:[1,0,1]
	v_pk_fma_f32 v[154:155], v[50:51], v[150:151], v[154:155] op_sel_hi:[1,0,1]
	v_pk_fma_f32 v[156:157], v[52:53], v[150:151], v[156:157] op_sel_hi:[1,0,1]
	v_pk_fma_f32 v[158:159], v[54:55], v[150:151], v[158:159] op_sel_hi:[1,0,1]
	v_pk_fma_f32 v[152:153], v[56:57], v[150:151], v[152:153] op_sel:[0,1,0]
	v_pk_fma_f32 v[154:155], v[58:59], v[150:151], v[154:155] op_sel:[0,1,0]
	v_pk_fma_f32 v[156:157], v[60:61], v[150:151], v[156:157] op_sel:[0,1,0]
	v_pk_fma_f32 v[158:159], v[62:63], v[150:151], v[158:159] op_sel:[0,1,0]
	v_lshlrev_b32_e32 v244, 16, v214
	v_and_b32_e32 v245, 0xffff0000, v214
	v_pk_mul_f32 v[244:245], v[244:245], v[152:153]
	v_cvt_pk_bf16_f32 v214, v244, v245
	v_lshlrev_b32_e32 v244, 16, v215
	v_and_b32_e32 v245, 0xffff0000, v215
	v_pk_mul_f32 v[244:245], v[244:245], v[154:155]
	v_cvt_pk_bf16_f32 v215, v244, v245
	v_lshlrev_b32_e32 v244, 16, v216
	v_and_b32_e32 v245, 0xffff0000, v216
	v_pk_mul_f32 v[244:245], v[244:245], v[156:157]
	v_cvt_pk_bf16_f32 v216, v244, v245
	v_lshlrev_b32_e32 v244, 16, v217
	v_and_b32_e32 v245, 0xffff0000, v217
	v_pk_mul_f32 v[244:245], v[244:245], v[158:159]
	v_cvt_pk_bf16_f32 v217, v244, v245
	global_store_dwordx4 v163, v[214:217], s[54:55]
	s_lshl_b32 s60, s57, 15
	s_add_u32 s52, s7, s60
	s_addc_u32 s53, s9, 0
	global_store_dwordx4 v135, v[0:3], s[52:53]
	global_store_dwordx4 v135, v[4:7], s[52:53] offset:16
	s_add_u32 s52, s52, 0x1000
	s_addc_u32 s53, s53, 0
	global_store_dwordx4 v135, v[8:11], s[52:53]
	global_store_dwordx4 v135, v[12:15], s[52:53] offset:16
	s_add_u32 s52, s52, 0x1000
	s_addc_u32 s53, s53, 0
	global_store_dwordx4 v135, v[16:19], s[52:53]
	global_store_dwordx4 v135, v[20:23], s[52:53] offset:16
	s_add_u32 s52, s52, 0x1000
	s_addc_u32 s53, s53, 0
	global_store_dwordx4 v135, v[24:27], s[52:53]
	global_store_dwordx4 v135, v[28:31], s[52:53] offset:16
	s_add_u32 s52, s52, 0x1000
	s_addc_u32 s53, s53, 0
	global_store_dwordx4 v135, v[32:35], s[52:53]
	global_store_dwordx4 v135, v[36:39], s[52:53] offset:16
	s_add_u32 s52, s52, 0x1000
	s_addc_u32 s53, s53, 0
	global_store_dwordx4 v135, v[40:43], s[52:53]
	global_store_dwordx4 v135, v[44:47], s[52:53] offset:16
	s_add_u32 s52, s52, 0x1000
	s_addc_u32 s53, s53, 0
	global_store_dwordx4 v135, v[48:51], s[52:53]
	global_store_dwordx4 v135, v[52:55], s[52:53] offset:16
	s_add_u32 s52, s52, 0x1000
	s_addc_u32 s53, s53, 0
	global_store_dwordx4 v135, v[56:59], s[52:53]
	global_store_dwordx4 v135, v[60:63], s[52:53] offset:16
	s_branch .LBB0_343
